# all four GEMM phases: hand-written k-loop (3-stage LDS-DMA ring, fragments double-buffered per k16 half, DMA issue interleaved with MFMAs, SALU addressing)
# speedup vs baseline: 1.0208x; 1.0208x over previous
.LBB0_535:
	s_or_saveexec_b64 s[0:1], s[0:1]
	v_mov_b32_e32 v127, 0
	v_mov_b64_e32 v[130:131], s[18:19]
	v_mov_b32_e32 v126, 0
	v_mov_b32_e32 v125, 0
	v_mov_b32_e32 v124, 0
	v_mov_b32_e32 v123, 0
	v_mov_b32_e32 v122, 0
	v_mov_b32_e32 v121, 0
	v_mov_b32_e32 v120, 0
	v_mov_b32_e32 v119, 0
	v_mov_b32_e32 v118, 0
	v_mov_b32_e32 v117, 0
	v_mov_b32_e32 v116, 0
	v_mov_b32_e32 v115, 0
	v_mov_b32_e32 v114, 0
	v_mov_b32_e32 v113, 0
	v_mov_b32_e32 v112, 0
	v_mov_b32_e32 v63, 0
	v_mov_b32_e32 v62, 0
	v_mov_b32_e32 v61, 0
	v_mov_b32_e32 v60, 0
	v_mov_b32_e32 v59, 0
	v_mov_b32_e32 v58, 0
	v_mov_b32_e32 v57, 0
	v_mov_b32_e32 v56, 0
	v_mov_b32_e32 v55, 0
	v_mov_b32_e32 v54, 0
	v_mov_b32_e32 v53, 0
	v_mov_b32_e32 v52, 0
	v_mov_b32_e32 v51, 0
	v_mov_b32_e32 v50, 0
	v_mov_b32_e32 v49, 0
	v_mov_b32_e32 v48, 0
	v_mov_b32_e32 v111, 0
	v_mov_b32_e32 v110, 0
	v_mov_b32_e32 v109, 0
	v_mov_b32_e32 v108, 0
	v_mov_b32_e32 v107, 0
	v_mov_b32_e32 v106, 0
	v_mov_b32_e32 v105, 0
	v_mov_b32_e32 v104, 0
	v_mov_b32_e32 v103, 0
	v_mov_b32_e32 v102, 0
	v_mov_b32_e32 v101, 0
	v_mov_b32_e32 v100, 0
	v_mov_b32_e32 v99, 0
	v_mov_b32_e32 v98, 0
	v_mov_b32_e32 v97, 0
	v_mov_b32_e32 v96, 0
	v_mov_b32_e32 v47, 0
	v_mov_b32_e32 v46, 0
	v_mov_b32_e32 v45, 0
	v_mov_b32_e32 v44, 0
	v_mov_b32_e32 v43, 0
	v_mov_b32_e32 v42, 0
	v_mov_b32_e32 v41, 0
	v_mov_b32_e32 v40, 0
	v_mov_b32_e32 v39, 0
	v_mov_b32_e32 v38, 0
	v_mov_b32_e32 v37, 0
	v_mov_b32_e32 v36, 0
	v_mov_b32_e32 v35, 0
	v_mov_b32_e32 v34, 0
	v_mov_b32_e32 v33, 0
	v_mov_b32_e32 v32, 0
	s_xor_b64 exec, exec, s[0:1]
	s_cbranch_execz .LBB0_539
	v_readfirstlane_b32 s78, v166
	v_readfirstlane_b32 s79, v168
	v_readfirstlane_b32 s76, v186
	v_mbcnt_lo_u32_b32 v244, -1, 0
	v_mbcnt_hi_u32_b32 v244, -1, v244
	s_nop 3
	s_lshl_b32 s78, s78, 14
	s_lshl_b32 s79, s79, 13
	s_add_u32 s72, s90, s78
	s_addc_u32 s73, s91, 0
	s_add_u32 s72, s72, 0xf0f0000
	s_addc_u32 s73, s73, 0
	s_add_u32 s74, s90, s79
	s_addc_u32 s75, s91, 0
	s_add_u32 s74, s74, 0x1b108000
	s_addc_u32 s75, s75, 0
	v_and_b32_e32 v245, 31, v244
	v_lshrrev_b32_e32 v246, 5, v244
	v_bfe_u32 v247, v244, 2, 2
	v_xor_b32_e32 v246, v246, v247
	v_lshlrev_b32_e32 v246, 4, v246
	v_lshl_or_b32 v245, v245, 6, v246
	v_lshrrev_b32_e32 v247, 10, v186
	v_lshrrev_b32_e32 v246, 1, v247
	v_lshl_or_b32 v128, v246, 11, v245
	v_and_b32_e32 v246, 1, v247
	v_lshl_or_b32 v167, v246, 12, v245
	v_or_b32_e32 v167, 0x4000, v167
	v_xor_b32_e32 v129, 32, v128
	v_xor_b32_e32 v169, 32, v167
	v_lshrrev_b32_e32 v245, 2, v244
	v_lshrrev_b32_e32 v246, 4, v244
	v_xor_b32_e32 v246, v246, v244
	v_and_b32_e32 v246, 3, v246
	v_lshlrev_b32_e32 v246, 4, v246
	v_lshl_or_b32 v245, v245, 6, v246
	v_or_b32_e32 v170, v245, v186
	v_add_u32_e32 v171, 0x1000, v170
	v_add_u32_e32 v180, 0x2000, v170
	v_add_u32_e32 v181, 0x3000, v170
	s_add_u32 m0, s76, 0x2000
	s_nop 0
	global_load_lds_dwordx4 v180, s[72:73]
	s_add_u32 m0, s76, 0x3000
	s_nop 0
	global_load_lds_dwordx4 v181, s[72:73]
	s_add_u32 m0, s76, 0x4000
	s_nop 0
	global_load_lds_dwordx4 v170, s[74:75]
	s_add_u32 m0, s76, 0x5000
	s_nop 0
	global_load_lds_dwordx4 v171, s[74:75]
	s_add_u32 s72, s72, 0x202000
	s_addc_u32 s73, s73, 0
	s_add_u32 s74, s74, 0x10000
	s_addc_u32 s75, s75, 0
	s_add_u32 m0, s76, 0x6000
	s_nop 0
	global_load_lds_dwordx4 v170, s[72:73]
	s_add_u32 m0, s76, 0x7000
	s_nop 0
	global_load_lds_dwordx4 v171, s[72:73]
	s_add_u32 m0, s76, 0x8000
	s_nop 0
	global_load_lds_dwordx4 v180, s[72:73]
	s_add_u32 m0, s76, 0x9000
	s_nop 0
	global_load_lds_dwordx4 v181, s[72:73]
	s_add_u32 m0, s76, 0xa000
	s_nop 0
	global_load_lds_dwordx4 v170, s[74:75]
	s_add_u32 m0, s76, 0xb000
	s_nop 0
	global_load_lds_dwordx4 v171, s[74:75]
	s_add_u32 s72, s72, 0x202000
	s_addc_u32 s73, s73, 0
	s_add_u32 s74, s74, 0x10000
	s_addc_u32 s75, s75, 0
	s_add_u32 m0, s76, 0xc000
	s_nop 0
	global_load_lds_dwordx4 v170, s[72:73]
	s_add_u32 m0, s76, 0xd000
	s_nop 0
	global_load_lds_dwordx4 v171, s[72:73]
	s_add_u32 m0, s76, 0xe000
	s_nop 0
	global_load_lds_dwordx4 v180, s[72:73]
	s_add_u32 m0, s76, 0xf000
	s_nop 0
	global_load_lds_dwordx4 v181, s[72:73]
	s_add_u32 m0, s76, 0x10000
	s_nop 0
	global_load_lds_dwordx4 v170, s[74:75]
	s_add_u32 m0, s76, 0x11000
	s_nop 0
	global_load_lds_dwordx4 v171, s[74:75]
	s_add_u32 s72, s72, 0x202000
	s_addc_u32 s73, s73, 0
	s_add_u32 s74, s74, 0x10000
	s_addc_u32 s75, s75, 0
	v_mov_b32_e32 v80, 0
	v_mov_b32_e32 v81, 0
	v_mov_b32_e32 v82, 0
	v_mov_b32_e32 v83, 0
	v_mov_b32_e32 v84, 0
	v_mov_b32_e32 v85, 0
	v_mov_b32_e32 v86, 0
	v_mov_b32_e32 v87, 0
	v_mov_b32_e32 v88, 0
	v_mov_b32_e32 v89, 0
	v_mov_b32_e32 v90, 0
	v_mov_b32_e32 v91, 0
	v_mov_b32_e32 v92, 0
	v_mov_b32_e32 v93, 0
	v_mov_b32_e32 v94, 0
	v_mov_b32_e32 v95, 0
	v_mov_b32_e32 v16, 0
	v_mov_b32_e32 v17, 0
	v_mov_b32_e32 v18, 0
	v_mov_b32_e32 v19, 0
	v_mov_b32_e32 v20, 0
	v_mov_b32_e32 v21, 0
	v_mov_b32_e32 v22, 0
	v_mov_b32_e32 v23, 0
	v_mov_b32_e32 v24, 0
	v_mov_b32_e32 v25, 0
	v_mov_b32_e32 v26, 0
	v_mov_b32_e32 v27, 0
	v_mov_b32_e32 v28, 0
	v_mov_b32_e32 v29, 0
	v_mov_b32_e32 v30, 0
	v_mov_b32_e32 v31, 0
	v_mov_b32_e32 v112, 0
	v_mov_b32_e32 v113, 0
	v_mov_b32_e32 v114, 0
	v_mov_b32_e32 v115, 0
	v_mov_b32_e32 v116, 0
	v_mov_b32_e32 v117, 0
	v_mov_b32_e32 v118, 0
	v_mov_b32_e32 v119, 0
	v_mov_b32_e32 v120, 0
	v_mov_b32_e32 v121, 0
	v_mov_b32_e32 v122, 0
	v_mov_b32_e32 v123, 0
	v_mov_b32_e32 v124, 0
	v_mov_b32_e32 v125, 0
	v_mov_b32_e32 v126, 0
	v_mov_b32_e32 v127, 0
	v_mov_b32_e32 v48, 0
	v_mov_b32_e32 v49, 0
	v_mov_b32_e32 v50, 0
	v_mov_b32_e32 v51, 0
	v_mov_b32_e32 v52, 0
	v_mov_b32_e32 v53, 0
	v_mov_b32_e32 v54, 0
	v_mov_b32_e32 v55, 0
	v_mov_b32_e32 v56, 0
	v_mov_b32_e32 v57, 0
	v_mov_b32_e32 v58, 0
	v_mov_b32_e32 v59, 0
	v_mov_b32_e32 v60, 0
	v_mov_b32_e32 v61, 0
	v_mov_b32_e32 v62, 0
	v_mov_b32_e32 v63, 0
	v_mov_b32_e32 v64, 0
	v_mov_b32_e32 v65, 0
	v_mov_b32_e32 v66, 0
	v_mov_b32_e32 v67, 0
	v_mov_b32_e32 v68, 0
	v_mov_b32_e32 v69, 0
	v_mov_b32_e32 v70, 0
	v_mov_b32_e32 v71, 0
	v_mov_b32_e32 v72, 0
	v_mov_b32_e32 v73, 0
	v_mov_b32_e32 v74, 0
	v_mov_b32_e32 v75, 0
	v_mov_b32_e32 v76, 0
	v_mov_b32_e32 v77, 0
	v_mov_b32_e32 v78, 0
	v_mov_b32_e32 v79, 0
	v_mov_b32_e32 v0, 0
	v_mov_b32_e32 v1, 0
	v_mov_b32_e32 v2, 0
	v_mov_b32_e32 v3, 0
	v_mov_b32_e32 v4, 0
	v_mov_b32_e32 v5, 0
	v_mov_b32_e32 v6, 0
	v_mov_b32_e32 v7, 0
	v_mov_b32_e32 v8, 0
	v_mov_b32_e32 v9, 0
	v_mov_b32_e32 v10, 0
	v_mov_b32_e32 v11, 0
	v_mov_b32_e32 v12, 0
	v_mov_b32_e32 v13, 0
	v_mov_b32_e32 v14, 0
	v_mov_b32_e32 v15, 0
	v_mov_b32_e32 v96, 0
	v_mov_b32_e32 v97, 0
	v_mov_b32_e32 v98, 0
	v_mov_b32_e32 v99, 0
	v_mov_b32_e32 v100, 0
	v_mov_b32_e32 v101, 0
	v_mov_b32_e32 v102, 0
	v_mov_b32_e32 v103, 0
	v_mov_b32_e32 v104, 0
	v_mov_b32_e32 v105, 0
	v_mov_b32_e32 v106, 0
	v_mov_b32_e32 v107, 0
	v_mov_b32_e32 v108, 0
	v_mov_b32_e32 v109, 0
	v_mov_b32_e32 v110, 0
	v_mov_b32_e32 v111, 0
	v_mov_b32_e32 v32, 0
	v_mov_b32_e32 v33, 0
	v_mov_b32_e32 v34, 0
	v_mov_b32_e32 v35, 0
	v_mov_b32_e32 v36, 0
	v_mov_b32_e32 v37, 0
	v_mov_b32_e32 v38, 0
	v_mov_b32_e32 v39, 0
	v_mov_b32_e32 v40, 0
	v_mov_b32_e32 v41, 0
	v_mov_b32_e32 v42, 0
	v_mov_b32_e32 v43, 0
	v_mov_b32_e32 v44, 0
	v_mov_b32_e32 v45, 0
	v_mov_b32_e32 v46, 0
	v_mov_b32_e32 v47, 0
	s_waitcnt vmcnt(12)
	s_barrier
	ds_read_b128 v[212:215], v167
	ds_read_b128 v[216:219], v167 offset:2048
	ds_read_b128 v[220:223], v128
	ds_read_b128 v[224:227], v128 offset:4096
	ds_read_b128 v[228:231], v128 offset:8192
	ds_read_b128 v[232:235], v128 offset:12288
	s_waitcnt lgkmcnt(0)
	s_mov_b32 s77, 13
.Lgemm_p3_loop:
	ds_read_b128 v[236:239], v169
	ds_read_b128 v[240:243], v169 offset:2048
	v_mfma_f32_32x32x16_bf16 v[80:95], v[212:215], v[220:223], v[80:95]
	ds_read_b128 v[132:135], v129
	ds_read_b128 v[136:139], v129 offset:4096
	v_mfma_f32_32x32x16_bf16 v[64:79], v[216:219], v[220:223], v[64:79]
	ds_read_b128 v[172:175], v129 offset:8192
	ds_read_b128 v[176:179], v129 offset:12288
	v_mfma_f32_32x32x16_bf16 v[16:31], v[212:215], v[224:227], v[16:31]
	v_mfma_f32_32x32x16_bf16 v[0:15], v[216:219], v[224:227], v[0:15]
	v_mfma_f32_32x32x16_bf16 v[112:127], v[212:215], v[228:231], v[112:127]
	v_mfma_f32_32x32x16_bf16 v[96:111], v[216:219], v[228:231], v[96:111]
	v_mfma_f32_32x32x16_bf16 v[48:63], v[212:215], v[232:235], v[48:63]
	v_mfma_f32_32x32x16_bf16 v[32:47], v[216:219], v[232:235], v[32:47]
	s_waitcnt lgkmcnt(0)
	s_waitcnt vmcnt(6)
	s_barrier
	ds_read_b128 v[212:215], v167 offset:24576
	ds_read_b128 v[216:219], v167 offset:26624
	v_mfma_f32_32x32x16_bf16 v[80:95], v[236:239], v[132:135], v[80:95]
	ds_read_b128 v[220:223], v128 offset:24576
	ds_read_b128 v[224:227], v128 offset:28672
	v_mfma_f32_32x32x16_bf16 v[64:79], v[240:243], v[132:135], v[64:79]
	ds_read_b128 v[228:231], v128 offset:32768
	ds_read_b128 v[232:235], v128 offset:36864
	v_mfma_f32_32x32x16_bf16 v[16:31], v[236:239], v[136:139], v[16:31]
	s_add_u32 m0, s76, 0x0
	v_mfma_f32_32x32x16_bf16 v[0:15], v[240:243], v[136:139], v[0:15]
	global_load_lds_dwordx4 v170, s[72:73]
	s_add_u32 m0, s76, 0x1000
	v_mfma_f32_32x32x16_bf16 v[112:127], v[236:239], v[172:175], v[112:127]
	global_load_lds_dwordx4 v171, s[72:73]
	s_add_u32 m0, s76, 0x2000
	v_mfma_f32_32x32x16_bf16 v[96:111], v[240:243], v[172:175], v[96:111]
	global_load_lds_dwordx4 v180, s[72:73]
	s_add_u32 m0, s76, 0x3000
	v_mfma_f32_32x32x16_bf16 v[48:63], v[236:239], v[176:179], v[48:63]
	global_load_lds_dwordx4 v181, s[72:73]
	s_add_u32 m0, s76, 0x4000
	v_mfma_f32_32x32x16_bf16 v[32:47], v[240:243], v[176:179], v[32:47]
	global_load_lds_dwordx4 v170, s[74:75]
	s_add_u32 m0, s76, 0x5000
	s_add_u32 s72, s72, 0x202000
	s_addc_u32 s73, s73, 0
	global_load_lds_dwordx4 v171, s[74:75]
	s_add_u32 s74, s74, 0x10000
	s_addc_u32 s75, s75, 0
	s_waitcnt lgkmcnt(0)
	ds_read_b128 v[236:239], v169 offset:24576
	ds_read_b128 v[240:243], v169 offset:26624
	v_mfma_f32_32x32x16_bf16 v[80:95], v[212:215], v[220:223], v[80:95]
	ds_read_b128 v[132:135], v129 offset:24576
	ds_read_b128 v[136:139], v129 offset:28672
	v_mfma_f32_32x32x16_bf16 v[64:79], v[216:219], v[220:223], v[64:79]
	ds_read_b128 v[172:175], v129 offset:32768
	ds_read_b128 v[176:179], v129 offset:36864
	v_mfma_f32_32x32x16_bf16 v[16:31], v[212:215], v[224:227], v[16:31]
	v_mfma_f32_32x32x16_bf16 v[0:15], v[216:219], v[224:227], v[0:15]
	v_mfma_f32_32x32x16_bf16 v[112:127], v[212:215], v[228:231], v[112:127]
	v_mfma_f32_32x32x16_bf16 v[96:111], v[216:219], v[228:231], v[96:111]
	v_mfma_f32_32x32x16_bf16 v[48:63], v[212:215], v[232:235], v[48:63]
	v_mfma_f32_32x32x16_bf16 v[32:47], v[216:219], v[232:235], v[32:47]
	s_waitcnt lgkmcnt(0)
	s_waitcnt vmcnt(6)
	s_barrier
	ds_read_b128 v[212:215], v167 offset:49152
	ds_read_b128 v[216:219], v167 offset:51200
	v_mfma_f32_32x32x16_bf16 v[80:95], v[236:239], v[132:135], v[80:95]
	ds_read_b128 v[220:223], v128 offset:49152
	ds_read_b128 v[224:227], v128 offset:53248
	v_mfma_f32_32x32x16_bf16 v[64:79], v[240:243], v[132:135], v[64:79]
	ds_read_b128 v[228:231], v128 offset:57344
	ds_read_b128 v[232:235], v128 offset:61440
	v_mfma_f32_32x32x16_bf16 v[16:31], v[236:239], v[136:139], v[16:31]
	s_add_u32 m0, s76, 0x6000
	v_mfma_f32_32x32x16_bf16 v[0:15], v[240:243], v[136:139], v[0:15]
	global_load_lds_dwordx4 v170, s[72:73]
	s_add_u32 m0, s76, 0x7000
	v_mfma_f32_32x32x16_bf16 v[112:127], v[236:239], v[172:175], v[112:127]
	global_load_lds_dwordx4 v171, s[72:73]
	s_add_u32 m0, s76, 0x8000
	v_mfma_f32_32x32x16_bf16 v[96:111], v[240:243], v[172:175], v[96:111]
	global_load_lds_dwordx4 v180, s[72:73]
	s_add_u32 m0, s76, 0x9000
	v_mfma_f32_32x32x16_bf16 v[48:63], v[236:239], v[176:179], v[48:63]
	global_load_lds_dwordx4 v181, s[72:73]
	s_add_u32 m0, s76, 0xa000
	v_mfma_f32_32x32x16_bf16 v[32:47], v[240:243], v[176:179], v[32:47]
	global_load_lds_dwordx4 v170, s[74:75]
	s_add_u32 m0, s76, 0xb000
	s_add_u32 s72, s72, 0x202000
	s_addc_u32 s73, s73, 0
	global_load_lds_dwordx4 v171, s[74:75]
	s_add_u32 s74, s74, 0x10000
	s_addc_u32 s75, s75, 0
	s_waitcnt lgkmcnt(0)
	ds_read_b128 v[236:239], v169 offset:49152
	ds_read_b128 v[240:243], v169 offset:51200
	v_mfma_f32_32x32x16_bf16 v[80:95], v[212:215], v[220:223], v[80:95]
	ds_read_b128 v[132:135], v129 offset:49152
	ds_read_b128 v[136:139], v129 offset:53248
	v_mfma_f32_32x32x16_bf16 v[64:79], v[216:219], v[220:223], v[64:79]
	ds_read_b128 v[172:175], v129 offset:57344
	ds_read_b128 v[176:179], v129 offset:61440
	v_mfma_f32_32x32x16_bf16 v[16:31], v[212:215], v[224:227], v[16:31]
	v_mfma_f32_32x32x16_bf16 v[0:15], v[216:219], v[224:227], v[0:15]
	v_mfma_f32_32x32x16_bf16 v[112:127], v[212:215], v[228:231], v[112:127]
	v_mfma_f32_32x32x16_bf16 v[96:111], v[216:219], v[228:231], v[96:111]
	v_mfma_f32_32x32x16_bf16 v[48:63], v[212:215], v[232:235], v[48:63]
	v_mfma_f32_32x32x16_bf16 v[32:47], v[216:219], v[232:235], v[32:47]
	s_waitcnt lgkmcnt(0)
	s_waitcnt vmcnt(6)
	s_barrier
	ds_read_b128 v[212:215], v167
	ds_read_b128 v[216:219], v167 offset:2048
	v_mfma_f32_32x32x16_bf16 v[80:95], v[236:239], v[132:135], v[80:95]
	ds_read_b128 v[220:223], v128
	ds_read_b128 v[224:227], v128 offset:4096
	v_mfma_f32_32x32x16_bf16 v[64:79], v[240:243], v[132:135], v[64:79]
	ds_read_b128 v[228:231], v128 offset:8192
	ds_read_b128 v[232:235], v128 offset:12288
	v_mfma_f32_32x32x16_bf16 v[16:31], v[236:239], v[136:139], v[16:31]
	s_add_u32 m0, s76, 0xc000
	v_mfma_f32_32x32x16_bf16 v[0:15], v[240:243], v[136:139], v[0:15]
	global_load_lds_dwordx4 v170, s[72:73]
	s_add_u32 m0, s76, 0xd000
	v_mfma_f32_32x32x16_bf16 v[112:127], v[236:239], v[172:175], v[112:127]
	global_load_lds_dwordx4 v171, s[72:73]
	s_add_u32 m0, s76, 0xe000
	v_mfma_f32_32x32x16_bf16 v[96:111], v[240:243], v[172:175], v[96:111]
	global_load_lds_dwordx4 v180, s[72:73]
	s_add_u32 m0, s76, 0xf000
	v_mfma_f32_32x32x16_bf16 v[48:63], v[236:239], v[176:179], v[48:63]
	global_load_lds_dwordx4 v181, s[72:73]
	s_add_u32 m0, s76, 0x10000
	v_mfma_f32_32x32x16_bf16 v[32:47], v[240:243], v[176:179], v[32:47]
	global_load_lds_dwordx4 v170, s[74:75]
	s_add_u32 m0, s76, 0x11000
	s_add_u32 s72, s72, 0x202000
	s_addc_u32 s73, s73, 0
	global_load_lds_dwordx4 v171, s[74:75]
	s_add_u32 s74, s74, 0x10000
	s_addc_u32 s75, s75, 0
	s_waitcnt lgkmcnt(0)
	s_sub_i32 s77, s77, 1
	s_cmp_lg_u32 s77, 0
	s_cbranch_scc1 .Lgemm_p3_loop
	ds_read_b128 v[236:239], v169
	ds_read_b128 v[240:243], v169 offset:2048
	v_mfma_f32_32x32x16_bf16 v[80:95], v[212:215], v[220:223], v[80:95]
	ds_read_b128 v[132:135], v129
	ds_read_b128 v[136:139], v129 offset:4096
	v_mfma_f32_32x32x16_bf16 v[64:79], v[216:219], v[220:223], v[64:79]
	ds_read_b128 v[172:175], v129 offset:8192
	ds_read_b128 v[176:179], v129 offset:12288
	v_mfma_f32_32x32x16_bf16 v[16:31], v[212:215], v[224:227], v[16:31]
	v_mfma_f32_32x32x16_bf16 v[0:15], v[216:219], v[224:227], v[0:15]
	v_mfma_f32_32x32x16_bf16 v[112:127], v[212:215], v[228:231], v[112:127]
	v_mfma_f32_32x32x16_bf16 v[96:111], v[216:219], v[228:231], v[96:111]
	v_mfma_f32_32x32x16_bf16 v[48:63], v[212:215], v[232:235], v[48:63]
	v_mfma_f32_32x32x16_bf16 v[32:47], v[216:219], v[232:235], v[32:47]
	s_waitcnt lgkmcnt(0)
	s_waitcnt vmcnt(6)
	s_barrier
	ds_read_b128 v[212:215], v167 offset:24576
	ds_read_b128 v[216:219], v167 offset:26624
	v_mfma_f32_32x32x16_bf16 v[80:95], v[236:239], v[132:135], v[80:95]
	ds_read_b128 v[220:223], v128 offset:24576
	ds_read_b128 v[224:227], v128 offset:28672
	v_mfma_f32_32x32x16_bf16 v[64:79], v[240:243], v[132:135], v[64:79]
	ds_read_b128 v[228:231], v128 offset:32768
	ds_read_b128 v[232:235], v128 offset:36864
	v_mfma_f32_32x32x16_bf16 v[16:31], v[236:239], v[136:139], v[16:31]
	s_add_u32 m0, s76, 0x0
	v_mfma_f32_32x32x16_bf16 v[0:15], v[240:243], v[136:139], v[0:15]
	global_load_lds_dwordx4 v170, s[72:73]
	s_add_u32 m0, s76, 0x1000
	v_mfma_f32_32x32x16_bf16 v[112:127], v[236:239], v[172:175], v[112:127]
	global_load_lds_dwordx4 v171, s[72:73]
	s_add_u32 m0, s76, 0x2000
	v_mfma_f32_32x32x16_bf16 v[96:111], v[240:243], v[172:175], v[96:111]
	global_load_lds_dwordx4 v180, s[72:73]
	s_add_u32 m0, s76, 0x3000
	v_mfma_f32_32x32x16_bf16 v[48:63], v[236:239], v[176:179], v[48:63]
	global_load_lds_dwordx4 v181, s[72:73]
	s_add_u32 m0, s76, 0x4000
	v_mfma_f32_32x32x16_bf16 v[32:47], v[240:243], v[176:179], v[32:47]
	global_load_lds_dwordx4 v170, s[74:75]
	s_add_u32 m0, s76, 0x5000
	s_add_u32 s72, s72, 0x202000
	s_addc_u32 s73, s73, 0
	global_load_lds_dwordx4 v171, s[74:75]
	s_add_u32 s74, s74, 0x10000
	s_addc_u32 s75, s75, 0
	s_waitcnt lgkmcnt(0)
	ds_read_b128 v[236:239], v169 offset:24576
	ds_read_b128 v[240:243], v169 offset:26624
	v_mfma_f32_32x32x16_bf16 v[80:95], v[212:215], v[220:223], v[80:95]
	ds_read_b128 v[132:135], v129 offset:24576
	ds_read_b128 v[136:139], v129 offset:28672
	v_mfma_f32_32x32x16_bf16 v[64:79], v[216:219], v[220:223], v[64:79]
	ds_read_b128 v[172:175], v129 offset:32768
	ds_read_b128 v[176:179], v129 offset:36864
	v_mfma_f32_32x32x16_bf16 v[16:31], v[212:215], v[224:227], v[16:31]
	v_mfma_f32_32x32x16_bf16 v[0:15], v[216:219], v[224:227], v[0:15]
	v_mfma_f32_32x32x16_bf16 v[112:127], v[212:215], v[228:231], v[112:127]
	v_mfma_f32_32x32x16_bf16 v[96:111], v[216:219], v[228:231], v[96:111]
	v_mfma_f32_32x32x16_bf16 v[48:63], v[212:215], v[232:235], v[48:63]
	v_mfma_f32_32x32x16_bf16 v[32:47], v[216:219], v[232:235], v[32:47]
	s_waitcnt lgkmcnt(0)
	s_waitcnt vmcnt(6)
	s_barrier
	ds_read_b128 v[212:215], v167 offset:49152
	ds_read_b128 v[216:219], v167 offset:51200
	v_mfma_f32_32x32x16_bf16 v[80:95], v[236:239], v[132:135], v[80:95]
	ds_read_b128 v[220:223], v128 offset:49152
	ds_read_b128 v[224:227], v128 offset:53248
	v_mfma_f32_32x32x16_bf16 v[64:79], v[240:243], v[132:135], v[64:79]
	ds_read_b128 v[228:231], v128 offset:57344
	ds_read_b128 v[232:235], v128 offset:61440
	v_mfma_f32_32x32x16_bf16 v[16:31], v[236:239], v[136:139], v[16:31]
	s_add_u32 m0, s76, 0x6000
	v_mfma_f32_32x32x16_bf16 v[0:15], v[240:243], v[136:139], v[0:15]
	global_load_lds_dwordx4 v170, s[72:73]
	s_add_u32 m0, s76, 0x7000
	v_mfma_f32_32x32x16_bf16 v[112:127], v[236:239], v[172:175], v[112:127]
	global_load_lds_dwordx4 v171, s[72:73]
	s_add_u32 m0, s76, 0x8000
	v_mfma_f32_32x32x16_bf16 v[96:111], v[240:243], v[172:175], v[96:111]
	global_load_lds_dwordx4 v180, s[72:73]
	s_add_u32 m0, s76, 0x9000
	v_mfma_f32_32x32x16_bf16 v[48:63], v[236:239], v[176:179], v[48:63]
	global_load_lds_dwordx4 v181, s[72:73]
	s_add_u32 m0, s76, 0xa000
	v_mfma_f32_32x32x16_bf16 v[32:47], v[240:243], v[176:179], v[32:47]
	global_load_lds_dwordx4 v170, s[74:75]
	s_add_u32 m0, s76, 0xb000
	s_add_u32 s72, s72, 0x202000
	s_addc_u32 s73, s73, 0
	global_load_lds_dwordx4 v171, s[74:75]
	s_add_u32 s74, s74, 0x10000
	s_addc_u32 s75, s75, 0
	s_waitcnt lgkmcnt(0)
	ds_read_b128 v[236:239], v169 offset:49152
	ds_read_b128 v[240:243], v169 offset:51200
	v_mfma_f32_32x32x16_bf16 v[80:95], v[212:215], v[220:223], v[80:95]
	ds_read_b128 v[132:135], v129 offset:49152
	ds_read_b128 v[136:139], v129 offset:53248
	v_mfma_f32_32x32x16_bf16 v[64:79], v[216:219], v[220:223], v[64:79]
	ds_read_b128 v[172:175], v129 offset:57344
	ds_read_b128 v[176:179], v129 offset:61440
	v_mfma_f32_32x32x16_bf16 v[16:31], v[212:215], v[224:227], v[16:31]
	v_mfma_f32_32x32x16_bf16 v[0:15], v[216:219], v[224:227], v[0:15]
	v_mfma_f32_32x32x16_bf16 v[112:127], v[212:215], v[228:231], v[112:127]
	v_mfma_f32_32x32x16_bf16 v[96:111], v[216:219], v[228:231], v[96:111]
	v_mfma_f32_32x32x16_bf16 v[48:63], v[212:215], v[232:235], v[48:63]
	v_mfma_f32_32x32x16_bf16 v[32:47], v[216:219], v[232:235], v[32:47]
	s_waitcnt lgkmcnt(0)
	s_waitcnt vmcnt(6)
	s_barrier
	ds_read_b128 v[212:215], v167
	ds_read_b128 v[216:219], v167 offset:2048
	v_mfma_f32_32x32x16_bf16 v[80:95], v[236:239], v[132:135], v[80:95]
	ds_read_b128 v[220:223], v128
	ds_read_b128 v[224:227], v128 offset:4096
	v_mfma_f32_32x32x16_bf16 v[64:79], v[240:243], v[132:135], v[64:79]
	ds_read_b128 v[228:231], v128 offset:8192
	ds_read_b128 v[232:235], v128 offset:12288
	v_mfma_f32_32x32x16_bf16 v[16:31], v[236:239], v[136:139], v[16:31]
	v_mfma_f32_32x32x16_bf16 v[0:15], v[240:243], v[136:139], v[0:15]
	v_mfma_f32_32x32x16_bf16 v[112:127], v[236:239], v[172:175], v[112:127]
	v_mfma_f32_32x32x16_bf16 v[96:111], v[240:243], v[172:175], v[96:111]
	v_mfma_f32_32x32x16_bf16 v[48:63], v[236:239], v[176:179], v[48:63]
	v_mfma_f32_32x32x16_bf16 v[32:47], v[240:243], v[176:179], v[32:47]
	s_waitcnt lgkmcnt(0)
	ds_read_b128 v[236:239], v169
	ds_read_b128 v[240:243], v169 offset:2048
	v_mfma_f32_32x32x16_bf16 v[80:95], v[212:215], v[220:223], v[80:95]
	ds_read_b128 v[132:135], v129
	ds_read_b128 v[136:139], v129 offset:4096
	v_mfma_f32_32x32x16_bf16 v[64:79], v[216:219], v[220:223], v[64:79]
	ds_read_b128 v[172:175], v129 offset:8192
	ds_read_b128 v[176:179], v129 offset:12288
	v_mfma_f32_32x32x16_bf16 v[16:31], v[212:215], v[224:227], v[16:31]
	v_mfma_f32_32x32x16_bf16 v[0:15], v[216:219], v[224:227], v[0:15]
	v_mfma_f32_32x32x16_bf16 v[112:127], v[212:215], v[228:231], v[112:127]
	v_mfma_f32_32x32x16_bf16 v[96:111], v[216:219], v[228:231], v[96:111]
	v_mfma_f32_32x32x16_bf16 v[48:63], v[212:215], v[232:235], v[48:63]
	v_mfma_f32_32x32x16_bf16 v[32:47], v[216:219], v[232:235], v[32:47]
	s_waitcnt lgkmcnt(0)
	s_waitcnt vmcnt(0)
	s_barrier
	ds_read_b128 v[212:215], v167 offset:24576
	ds_read_b128 v[216:219], v167 offset:26624
	v_mfma_f32_32x32x16_bf16 v[80:95], v[236:239], v[132:135], v[80:95]
	ds_read_b128 v[220:223], v128 offset:24576
	ds_read_b128 v[224:227], v128 offset:28672
	v_mfma_f32_32x32x16_bf16 v[64:79], v[240:243], v[132:135], v[64:79]
	ds_read_b128 v[228:231], v128 offset:32768
	ds_read_b128 v[232:235], v128 offset:36864
	v_mfma_f32_32x32x16_bf16 v[16:31], v[236:239], v[136:139], v[16:31]
	v_mfma_f32_32x32x16_bf16 v[0:15], v[240:243], v[136:139], v[0:15]
	v_mfma_f32_32x32x16_bf16 v[112:127], v[236:239], v[172:175], v[112:127]
	v_mfma_f32_32x32x16_bf16 v[96:111], v[240:243], v[172:175], v[96:111]
	v_mfma_f32_32x32x16_bf16 v[48:63], v[236:239], v[176:179], v[48:63]
	v_mfma_f32_32x32x16_bf16 v[32:47], v[240:243], v[176:179], v[32:47]
	s_waitcnt lgkmcnt(0)
	ds_read_b128 v[236:239], v169 offset:24576
	ds_read_b128 v[240:243], v169 offset:26624
	v_mfma_f32_32x32x16_bf16 v[80:95], v[212:215], v[220:223], v[80:95]
	ds_read_b128 v[132:135], v129 offset:24576
	ds_read_b128 v[136:139], v129 offset:28672
	v_mfma_f32_32x32x16_bf16 v[64:79], v[216:219], v[220:223], v[64:79]
	ds_read_b128 v[172:175], v129 offset:32768
	ds_read_b128 v[176:179], v129 offset:36864
	v_mfma_f32_32x32x16_bf16 v[16:31], v[212:215], v[224:227], v[16:31]
	v_mfma_f32_32x32x16_bf16 v[0:15], v[216:219], v[224:227], v[0:15]
	v_mfma_f32_32x32x16_bf16 v[112:127], v[212:215], v[228:231], v[112:127]
	v_mfma_f32_32x32x16_bf16 v[96:111], v[216:219], v[228:231], v[96:111]
	v_mfma_f32_32x32x16_bf16 v[48:63], v[212:215], v[232:235], v[48:63]
	v_mfma_f32_32x32x16_bf16 v[32:47], v[216:219], v[232:235], v[32:47]
	s_waitcnt lgkmcnt(0)
	v_mfma_f32_32x32x16_bf16 v[80:95], v[236:239], v[132:135], v[80:95]
	v_mfma_f32_32x32x16_bf16 v[64:79], v[240:243], v[132:135], v[64:79]
	v_mfma_f32_32x32x16_bf16 v[16:31], v[236:239], v[136:139], v[16:31]
	v_mfma_f32_32x32x16_bf16 v[0:15], v[240:243], v[136:139], v[0:15]
	v_mfma_f32_32x32x16_bf16 v[112:127], v[236:239], v[172:175], v[112:127]
	v_mfma_f32_32x32x16_bf16 v[96:111], v[240:243], v[172:175], v[96:111]
	v_mfma_f32_32x32x16_bf16 v[48:63], v[236:239], v[176:179], v[48:63]
	v_mfma_f32_32x32x16_bf16 v[32:47], v[240:243], v[176:179], v[32:47]
	s_nop 15
	v_readlane_b32 s72, v254, 13
	v_readlane_b32 s73, v254, 14
	s_nop 1
	v_mov_b64_e32 v[130:131], s[72:73]

.LBB0_630:
	s_or_saveexec_b64 s[0:1], s[0:1]
	v_mov_b32_e32 v63, 0
	v_mov_b32_e32 v62, 0
	v_mov_b32_e32 v61, 0
	v_mov_b32_e32 v60, 0
	v_mov_b32_e32 v59, 0
	v_mov_b32_e32 v58, 0
	v_mov_b32_e32 v57, 0
	v_mov_b32_e32 v56, 0
	v_mov_b32_e32 v55, 0
	v_mov_b32_e32 v54, 0
	v_mov_b32_e32 v53, 0
	v_mov_b32_e32 v52, 0
	v_mov_b32_e32 v51, 0
	v_mov_b32_e32 v50, 0
	v_mov_b32_e32 v49, 0
	v_mov_b32_e32 v48, v63
	v_mov_b32_e32 v31, 0
	v_mov_b32_e32 v30, 0
	v_mov_b32_e32 v29, 0
	v_mov_b32_e32 v28, 0
	v_mov_b32_e32 v27, 0
	v_mov_b32_e32 v26, 0
	v_mov_b32_e32 v25, 0
	v_mov_b32_e32 v24, 0
	v_mov_b32_e32 v23, 0
	v_mov_b32_e32 v22, 0
	v_mov_b32_e32 v21, 0
	v_mov_b32_e32 v20, 0
	v_mov_b32_e32 v19, 0
	v_mov_b32_e32 v18, 0
	v_mov_b32_e32 v17, 0
	v_mov_b32_e32 v16, v63
	v_mov_b32_e32 v47, 0
	v_mov_b32_e32 v46, v63
	v_mov_b32_e32 v45, 0
	v_mov_b32_e32 v44, v63
	v_mov_b32_e32 v43, 0
	v_mov_b32_e32 v42, v63
	v_mov_b32_e32 v41, 0
	v_mov_b32_e32 v40, v63
	v_mov_b32_e32 v39, 0
	v_mov_b32_e32 v38, v63
	v_mov_b32_e32 v37, 0
	v_mov_b32_e32 v36, 0
	v_mov_b32_e32 v35, 0
	v_mov_b32_e32 v34, 0
	v_mov_b32_e32 v33, 0
	v_mov_b32_e32 v32, v63
	v_mov_b32_e32 v15, 0
	v_mov_b32_e32 v14, v63
	v_mov_b32_e32 v13, 0
	v_mov_b32_e32 v12, v63
	v_mov_b32_e32 v11, 0
	v_mov_b32_e32 v10, v63
	v_mov_b32_e32 v9, 0
	v_mov_b32_e32 v8, v63
	v_mov_b32_e32 v7, 0
	v_mov_b32_e32 v6, v63
	v_mov_b32_e32 v5, 0
	v_mov_b32_e32 v4, 0
	v_mov_b32_e32 v3, 0
	v_mov_b32_e32 v2, 0
	v_mov_b32_e32 v1, 0
	v_mov_b32_e32 v0, v63
	s_xor_b64 exec, exec, s[0:1]
	s_cbranch_execz .LBB0_634
	v_readfirstlane_b32 s10, v128
	v_readfirstlane_b32 s11, v130
	v_readfirstlane_b32 s8, v226
	v_mbcnt_lo_u32_b32 v192, -1, 0
	v_mbcnt_hi_u32_b32 v192, -1, v192
	s_nop 3
	s_lshl_b32 s10, s10, 14
	s_lshl_b32 s11, s11, 13
	s_add_u32 s4, s90, s10
	s_addc_u32 s5, s91, 0
	s_add_u32 s6, s90, s11
	s_addc_u32 s7, s91, 0
	s_add_u32 s6, s6, 0x1b3c8000
	s_addc_u32 s7, s7, 0
	v_and_b32_e32 v193, 31, v192
	v_lshrrev_b32_e32 v194, 5, v192
	v_bfe_u32 v195, v192, 2, 2
	v_xor_b32_e32 v194, v194, v195
	v_lshlrev_b32_e32 v194, 4, v194
	v_lshl_or_b32 v193, v193, 6, v194
	v_lshrrev_b32_e32 v195, 10, v226
	v_lshrrev_b32_e32 v194, 1, v195
	v_lshl_or_b32 v129, v194, 11, v193
	v_and_b32_e32 v194, 1, v195
	v_lshl_or_b32 v156, v194, 12, v193
	v_or_b32_e32 v156, 0x4000, v156
	v_xor_b32_e32 v131, 32, v129
	v_xor_b32_e32 v188, 32, v156
	v_lshrrev_b32_e32 v193, 2, v192
	v_lshrrev_b32_e32 v194, 4, v192
	v_xor_b32_e32 v194, v194, v192
	v_and_b32_e32 v194, 3, v194
	v_lshlrev_b32_e32 v194, 4, v194
	v_lshl_or_b32 v193, v193, 6, v194
	v_or_b32_e32 v189, v193, v226
	v_add_u32_e32 v252, 0x1000, v189
	v_add_u32_e32 v190, 0x2000, v189
	v_add_u32_e32 v191, 0x3000, v189
	s_add_u32 m0, s8, 0x2000
	s_nop 0
	global_load_lds_dwordx4 v190, s[4:5]
	s_add_u32 m0, s8, 0x3000
	s_nop 0
	global_load_lds_dwordx4 v191, s[4:5]
	s_add_u32 m0, s8, 0x4000
	s_nop 0
	global_load_lds_dwordx4 v189, s[6:7]
	s_add_u32 m0, s8, 0x5000
	s_nop 0
	global_load_lds_dwordx4 v252, s[6:7]
	s_add_u32 s4, s4, 0x202000
	s_addc_u32 s5, s5, 0
	s_add_u32 s6, s6, 0x40000
	s_addc_u32 s7, s7, 0
	s_add_u32 m0, s8, 0x6000
	s_nop 0
	global_load_lds_dwordx4 v189, s[4:5]
	s_add_u32 m0, s8, 0x7000
	s_nop 0
	global_load_lds_dwordx4 v252, s[4:5]
	s_add_u32 m0, s8, 0x8000
	s_nop 0
	global_load_lds_dwordx4 v190, s[4:5]
	s_add_u32 m0, s8, 0x9000
	s_nop 0
	global_load_lds_dwordx4 v191, s[4:5]
	s_add_u32 m0, s8, 0xa000
	s_nop 0
	global_load_lds_dwordx4 v189, s[6:7]
	s_add_u32 m0, s8, 0xb000
	s_nop 0
	global_load_lds_dwordx4 v252, s[6:7]
	s_add_u32 s4, s4, 0x202000
	s_addc_u32 s5, s5, 0
	s_add_u32 s6, s6, 0x40000
	s_addc_u32 s7, s7, 0
	s_add_u32 m0, s8, 0xc000
	s_nop 0
	global_load_lds_dwordx4 v189, s[4:5]
	s_add_u32 m0, s8, 0xd000
	s_nop 0
	global_load_lds_dwordx4 v252, s[4:5]
	s_add_u32 m0, s8, 0xe000
	s_nop 0
	global_load_lds_dwordx4 v190, s[4:5]
	s_add_u32 m0, s8, 0xf000
	s_nop 0
	global_load_lds_dwordx4 v191, s[4:5]
	s_add_u32 m0, s8, 0x10000
	s_nop 0
	global_load_lds_dwordx4 v189, s[6:7]
	s_add_u32 m0, s8, 0x11000
	s_nop 0
	global_load_lds_dwordx4 v252, s[6:7]
	s_add_u32 s4, s4, 0x202000
	s_addc_u32 s5, s5, 0
	s_add_u32 s6, s6, 0x40000
	s_addc_u32 s7, s7, 0
	v_mov_b32_e32 v112, 0
	v_mov_b32_e32 v113, 0
	v_mov_b32_e32 v114, 0
	v_mov_b32_e32 v115, 0
	v_mov_b32_e32 v116, 0
	v_mov_b32_e32 v117, 0
	v_mov_b32_e32 v118, 0
	v_mov_b32_e32 v119, 0
	v_mov_b32_e32 v120, 0
	v_mov_b32_e32 v121, 0
	v_mov_b32_e32 v122, 0
	v_mov_b32_e32 v123, 0
	v_mov_b32_e32 v124, 0
	v_mov_b32_e32 v125, 0
	v_mov_b32_e32 v126, 0
	v_mov_b32_e32 v127, 0
	v_mov_b32_e32 v80, 0
	v_mov_b32_e32 v81, 0
	v_mov_b32_e32 v82, 0
	v_mov_b32_e32 v83, 0
	v_mov_b32_e32 v84, 0
	v_mov_b32_e32 v85, 0
	v_mov_b32_e32 v86, 0
	v_mov_b32_e32 v87, 0
	v_mov_b32_e32 v88, 0
	v_mov_b32_e32 v89, 0
	v_mov_b32_e32 v90, 0
	v_mov_b32_e32 v91, 0
	v_mov_b32_e32 v92, 0
	v_mov_b32_e32 v93, 0
	v_mov_b32_e32 v94, 0
	v_mov_b32_e32 v95, 0
	v_mov_b32_e32 v48, 0
	v_mov_b32_e32 v49, 0
	v_mov_b32_e32 v50, 0
	v_mov_b32_e32 v51, 0
	v_mov_b32_e32 v52, 0
	v_mov_b32_e32 v53, 0
	v_mov_b32_e32 v54, 0
	v_mov_b32_e32 v55, 0
	v_mov_b32_e32 v56, 0
	v_mov_b32_e32 v57, 0
	v_mov_b32_e32 v58, 0
	v_mov_b32_e32 v59, 0
	v_mov_b32_e32 v60, 0
	v_mov_b32_e32 v61, 0
	v_mov_b32_e32 v62, 0
	v_mov_b32_e32 v63, 0
	v_mov_b32_e32 v16, 0
	v_mov_b32_e32 v17, 0
	v_mov_b32_e32 v18, 0
	v_mov_b32_e32 v19, 0
	v_mov_b32_e32 v20, 0
	v_mov_b32_e32 v21, 0
	v_mov_b32_e32 v22, 0
	v_mov_b32_e32 v23, 0
	v_mov_b32_e32 v24, 0
	v_mov_b32_e32 v25, 0
	v_mov_b32_e32 v26, 0
	v_mov_b32_e32 v27, 0
	v_mov_b32_e32 v28, 0
	v_mov_b32_e32 v29, 0
	v_mov_b32_e32 v30, 0
	v_mov_b32_e32 v31, 0
	v_mov_b32_e32 v96, 0
	v_mov_b32_e32 v97, 0
	v_mov_b32_e32 v98, 0
	v_mov_b32_e32 v99, 0
	v_mov_b32_e32 v100, 0
	v_mov_b32_e32 v101, 0
	v_mov_b32_e32 v102, 0
	v_mov_b32_e32 v103, 0
	v_mov_b32_e32 v104, 0
	v_mov_b32_e32 v105, 0
	v_mov_b32_e32 v106, 0
	v_mov_b32_e32 v107, 0
	v_mov_b32_e32 v108, 0
	v_mov_b32_e32 v109, 0
	v_mov_b32_e32 v110, 0
	v_mov_b32_e32 v111, 0
	v_mov_b32_e32 v64, 0
	v_mov_b32_e32 v65, 0
	v_mov_b32_e32 v66, 0
	v_mov_b32_e32 v67, 0
	v_mov_b32_e32 v68, 0
	v_mov_b32_e32 v69, 0
	v_mov_b32_e32 v70, 0
	v_mov_b32_e32 v71, 0
	v_mov_b32_e32 v72, 0
	v_mov_b32_e32 v73, 0
	v_mov_b32_e32 v74, 0
	v_mov_b32_e32 v75, 0
	v_mov_b32_e32 v76, 0
	v_mov_b32_e32 v77, 0
	v_mov_b32_e32 v78, 0
	v_mov_b32_e32 v79, 0
	v_mov_b32_e32 v32, 0
	v_mov_b32_e32 v33, 0
	v_mov_b32_e32 v34, 0
	v_mov_b32_e32 v35, 0
	v_mov_b32_e32 v36, 0
	v_mov_b32_e32 v37, 0
	v_mov_b32_e32 v38, 0
	v_mov_b32_e32 v39, 0
	v_mov_b32_e32 v40, 0
	v_mov_b32_e32 v41, 0
	v_mov_b32_e32 v42, 0
	v_mov_b32_e32 v43, 0
	v_mov_b32_e32 v44, 0
	v_mov_b32_e32 v45, 0
	v_mov_b32_e32 v46, 0
	v_mov_b32_e32 v47, 0
	v_mov_b32_e32 v0, 0
	v_mov_b32_e32 v1, 0
	v_mov_b32_e32 v2, 0
	v_mov_b32_e32 v3, 0
	v_mov_b32_e32 v4, 0
	v_mov_b32_e32 v5, 0
	v_mov_b32_e32 v6, 0
	v_mov_b32_e32 v7, 0
	v_mov_b32_e32 v8, 0
	v_mov_b32_e32 v9, 0
	v_mov_b32_e32 v10, 0
	v_mov_b32_e32 v11, 0
	v_mov_b32_e32 v12, 0
	v_mov_b32_e32 v13, 0
	v_mov_b32_e32 v14, 0
	v_mov_b32_e32 v15, 0
	s_waitcnt vmcnt(12)
	s_barrier
	ds_read_b128 v[132:135], v156
	ds_read_b128 v[136:139], v156 offset:2048
	ds_read_b128 v[140:143], v129
	ds_read_b128 v[180:183], v129 offset:4096
	ds_read_b128 v[184:187], v129 offset:8192
	ds_read_b128 v[236:239], v129 offset:12288
	s_waitcnt lgkmcnt(0)
	s_mov_b32 s9, 9
.Lgemm_p4_loop:
	ds_read_b128 v[240:243], v188
	ds_read_b128 v[244:247], v188 offset:2048
	v_mfma_f32_32x32x16_bf16 v[112:127], v[132:135], v[140:143], v[112:127]
	ds_read_b128 v[248:251], v131
	ds_read_b128 v[200:203], v131 offset:4096
	v_mfma_f32_32x32x16_bf16 v[96:111], v[136:139], v[140:143], v[96:111]
	ds_read_b128 v[204:207], v131 offset:8192
	ds_read_b128 v[208:211], v131 offset:12288
	v_mfma_f32_32x32x16_bf16 v[80:95], v[132:135], v[180:183], v[80:95]
	v_mfma_f32_32x32x16_bf16 v[64:79], v[136:139], v[180:183], v[64:79]
	v_mfma_f32_32x32x16_bf16 v[48:63], v[132:135], v[184:187], v[48:63]
	v_mfma_f32_32x32x16_bf16 v[32:47], v[136:139], v[184:187], v[32:47]
	v_mfma_f32_32x32x16_bf16 v[16:31], v[132:135], v[236:239], v[16:31]
	v_mfma_f32_32x32x16_bf16 v[0:15], v[136:139], v[236:239], v[0:15]
	s_waitcnt lgkmcnt(0)
	s_waitcnt vmcnt(6)
	s_barrier
	ds_read_b128 v[132:135], v156 offset:24576
	ds_read_b128 v[136:139], v156 offset:26624
	v_mfma_f32_32x32x16_bf16 v[112:127], v[240:243], v[248:251], v[112:127]
	ds_read_b128 v[140:143], v129 offset:24576
	ds_read_b128 v[180:183], v129 offset:28672
	v_mfma_f32_32x32x16_bf16 v[96:111], v[244:247], v[248:251], v[96:111]
	ds_read_b128 v[184:187], v129 offset:32768
	ds_read_b128 v[236:239], v129 offset:36864
	v_mfma_f32_32x32x16_bf16 v[80:95], v[240:243], v[200:203], v[80:95]
	s_add_u32 m0, s8, 0x0
	v_mfma_f32_32x32x16_bf16 v[64:79], v[244:247], v[200:203], v[64:79]
	global_load_lds_dwordx4 v189, s[4:5]
	s_add_u32 m0, s8, 0x1000
	v_mfma_f32_32x32x16_bf16 v[48:63], v[240:243], v[204:207], v[48:63]
	global_load_lds_dwordx4 v252, s[4:5]
	s_add_u32 m0, s8, 0x2000
	v_mfma_f32_32x32x16_bf16 v[32:47], v[244:247], v[204:207], v[32:47]
	global_load_lds_dwordx4 v190, s[4:5]
	s_add_u32 m0, s8, 0x3000
	v_mfma_f32_32x32x16_bf16 v[16:31], v[240:243], v[208:211], v[16:31]
	global_load_lds_dwordx4 v191, s[4:5]
	s_add_u32 m0, s8, 0x4000
	v_mfma_f32_32x32x16_bf16 v[0:15], v[244:247], v[208:211], v[0:15]
	global_load_lds_dwordx4 v189, s[6:7]
	s_add_u32 m0, s8, 0x5000
	s_add_u32 s4, s4, 0x202000
	s_addc_u32 s5, s5, 0
	global_load_lds_dwordx4 v252, s[6:7]
	s_add_u32 s6, s6, 0x40000
	s_addc_u32 s7, s7, 0
	s_waitcnt lgkmcnt(0)
	ds_read_b128 v[240:243], v188 offset:24576
	ds_read_b128 v[244:247], v188 offset:26624
	v_mfma_f32_32x32x16_bf16 v[112:127], v[132:135], v[140:143], v[112:127]
	ds_read_b128 v[248:251], v131 offset:24576
	ds_read_b128 v[200:203], v131 offset:28672
	v_mfma_f32_32x32x16_bf16 v[96:111], v[136:139], v[140:143], v[96:111]
	ds_read_b128 v[204:207], v131 offset:32768
	ds_read_b128 v[208:211], v131 offset:36864
	v_mfma_f32_32x32x16_bf16 v[80:95], v[132:135], v[180:183], v[80:95]
	v_mfma_f32_32x32x16_bf16 v[64:79], v[136:139], v[180:183], v[64:79]
	v_mfma_f32_32x32x16_bf16 v[48:63], v[132:135], v[184:187], v[48:63]
	v_mfma_f32_32x32x16_bf16 v[32:47], v[136:139], v[184:187], v[32:47]
	v_mfma_f32_32x32x16_bf16 v[16:31], v[132:135], v[236:239], v[16:31]
	v_mfma_f32_32x32x16_bf16 v[0:15], v[136:139], v[236:239], v[0:15]
	s_waitcnt lgkmcnt(0)
	s_waitcnt vmcnt(6)
	s_barrier
	ds_read_b128 v[132:135], v156 offset:49152
	ds_read_b128 v[136:139], v156 offset:51200
	v_mfma_f32_32x32x16_bf16 v[112:127], v[240:243], v[248:251], v[112:127]
	ds_read_b128 v[140:143], v129 offset:49152
	ds_read_b128 v[180:183], v129 offset:53248
	v_mfma_f32_32x32x16_bf16 v[96:111], v[244:247], v[248:251], v[96:111]
	ds_read_b128 v[184:187], v129 offset:57344
	ds_read_b128 v[236:239], v129 offset:61440
	v_mfma_f32_32x32x16_bf16 v[80:95], v[240:243], v[200:203], v[80:95]
	s_add_u32 m0, s8, 0x6000
	v_mfma_f32_32x32x16_bf16 v[64:79], v[244:247], v[200:203], v[64:79]
	global_load_lds_dwordx4 v189, s[4:5]
	s_add_u32 m0, s8, 0x7000
	v_mfma_f32_32x32x16_bf16 v[48:63], v[240:243], v[204:207], v[48:63]
	global_load_lds_dwordx4 v252, s[4:5]
	s_add_u32 m0, s8, 0x8000
	v_mfma_f32_32x32x16_bf16 v[32:47], v[244:247], v[204:207], v[32:47]
	global_load_lds_dwordx4 v190, s[4:5]
	s_add_u32 m0, s8, 0x9000
	v_mfma_f32_32x32x16_bf16 v[16:31], v[240:243], v[208:211], v[16:31]
	global_load_lds_dwordx4 v191, s[4:5]
	s_add_u32 m0, s8, 0xa000
	v_mfma_f32_32x32x16_bf16 v[0:15], v[244:247], v[208:211], v[0:15]
	global_load_lds_dwordx4 v189, s[6:7]
	s_add_u32 m0, s8, 0xb000
	s_add_u32 s4, s4, 0x202000
	s_addc_u32 s5, s5, 0
	global_load_lds_dwordx4 v252, s[6:7]
	s_add_u32 s6, s6, 0x40000
	s_addc_u32 s7, s7, 0
	s_waitcnt lgkmcnt(0)
	ds_read_b128 v[240:243], v188 offset:49152
	ds_read_b128 v[244:247], v188 offset:51200
	v_mfma_f32_32x32x16_bf16 v[112:127], v[132:135], v[140:143], v[112:127]
	ds_read_b128 v[248:251], v131 offset:49152
	ds_read_b128 v[200:203], v131 offset:53248
	v_mfma_f32_32x32x16_bf16 v[96:111], v[136:139], v[140:143], v[96:111]
	ds_read_b128 v[204:207], v131 offset:57344
	ds_read_b128 v[208:211], v131 offset:61440
	v_mfma_f32_32x32x16_bf16 v[80:95], v[132:135], v[180:183], v[80:95]
	v_mfma_f32_32x32x16_bf16 v[64:79], v[136:139], v[180:183], v[64:79]
	v_mfma_f32_32x32x16_bf16 v[48:63], v[132:135], v[184:187], v[48:63]
	v_mfma_f32_32x32x16_bf16 v[32:47], v[136:139], v[184:187], v[32:47]
	v_mfma_f32_32x32x16_bf16 v[16:31], v[132:135], v[236:239], v[16:31]
	v_mfma_f32_32x32x16_bf16 v[0:15], v[136:139], v[236:239], v[0:15]
	s_waitcnt lgkmcnt(0)
	s_waitcnt vmcnt(6)
	s_barrier
	ds_read_b128 v[132:135], v156
	ds_read_b128 v[136:139], v156 offset:2048
	v_mfma_f32_32x32x16_bf16 v[112:127], v[240:243], v[248:251], v[112:127]
	ds_read_b128 v[140:143], v129
	ds_read_b128 v[180:183], v129 offset:4096
	v_mfma_f32_32x32x16_bf16 v[96:111], v[244:247], v[248:251], v[96:111]
	ds_read_b128 v[184:187], v129 offset:8192
	ds_read_b128 v[236:239], v129 offset:12288
	v_mfma_f32_32x32x16_bf16 v[80:95], v[240:243], v[200:203], v[80:95]
	s_add_u32 m0, s8, 0xc000
	v_mfma_f32_32x32x16_bf16 v[64:79], v[244:247], v[200:203], v[64:79]
	global_load_lds_dwordx4 v189, s[4:5]
	s_add_u32 m0, s8, 0xd000
	v_mfma_f32_32x32x16_bf16 v[48:63], v[240:243], v[204:207], v[48:63]
	global_load_lds_dwordx4 v252, s[4:5]
	s_add_u32 m0, s8, 0xe000
	v_mfma_f32_32x32x16_bf16 v[32:47], v[244:247], v[204:207], v[32:47]
	global_load_lds_dwordx4 v190, s[4:5]
	s_add_u32 m0, s8, 0xf000
	v_mfma_f32_32x32x16_bf16 v[16:31], v[240:243], v[208:211], v[16:31]
	global_load_lds_dwordx4 v191, s[4:5]
	s_add_u32 m0, s8, 0x10000
	v_mfma_f32_32x32x16_bf16 v[0:15], v[244:247], v[208:211], v[0:15]
	global_load_lds_dwordx4 v189, s[6:7]
	s_add_u32 m0, s8, 0x11000
	s_add_u32 s4, s4, 0x202000
	s_addc_u32 s5, s5, 0
	global_load_lds_dwordx4 v252, s[6:7]
	s_add_u32 s6, s6, 0x40000
	s_addc_u32 s7, s7, 0
	s_waitcnt lgkmcnt(0)
	s_sub_i32 s9, s9, 1
	s_cmp_lg_u32 s9, 0
	s_cbranch_scc1 .Lgemm_p4_loop
	ds_read_b128 v[240:243], v188
	ds_read_b128 v[244:247], v188 offset:2048
	v_mfma_f32_32x32x16_bf16 v[112:127], v[132:135], v[140:143], v[112:127]
	ds_read_b128 v[248:251], v131
	ds_read_b128 v[200:203], v131 offset:4096
	v_mfma_f32_32x32x16_bf16 v[96:111], v[136:139], v[140:143], v[96:111]
	ds_read_b128 v[204:207], v131 offset:8192
	ds_read_b128 v[208:211], v131 offset:12288
	v_mfma_f32_32x32x16_bf16 v[80:95], v[132:135], v[180:183], v[80:95]
	v_mfma_f32_32x32x16_bf16 v[64:79], v[136:139], v[180:183], v[64:79]
	v_mfma_f32_32x32x16_bf16 v[48:63], v[132:135], v[184:187], v[48:63]
	v_mfma_f32_32x32x16_bf16 v[32:47], v[136:139], v[184:187], v[32:47]
	v_mfma_f32_32x32x16_bf16 v[16:31], v[132:135], v[236:239], v[16:31]
	v_mfma_f32_32x32x16_bf16 v[0:15], v[136:139], v[236:239], v[0:15]
	s_waitcnt lgkmcnt(0)
	s_waitcnt vmcnt(6)
	s_barrier
	ds_read_b128 v[132:135], v156 offset:24576
	ds_read_b128 v[136:139], v156 offset:26624
	v_mfma_f32_32x32x16_bf16 v[112:127], v[240:243], v[248:251], v[112:127]
	ds_read_b128 v[140:143], v129 offset:24576
	ds_read_b128 v[180:183], v129 offset:28672
	v_mfma_f32_32x32x16_bf16 v[96:111], v[244:247], v[248:251], v[96:111]
	ds_read_b128 v[184:187], v129 offset:32768
	ds_read_b128 v[236:239], v129 offset:36864
	v_mfma_f32_32x32x16_bf16 v[80:95], v[240:243], v[200:203], v[80:95]
	s_add_u32 m0, s8, 0x0
	v_mfma_f32_32x32x16_bf16 v[64:79], v[244:247], v[200:203], v[64:79]
	global_load_lds_dwordx4 v189, s[4:5]
	s_add_u32 m0, s8, 0x1000
	v_mfma_f32_32x32x16_bf16 v[48:63], v[240:243], v[204:207], v[48:63]
	global_load_lds_dwordx4 v252, s[4:5]
	s_add_u32 m0, s8, 0x2000
	v_mfma_f32_32x32x16_bf16 v[32:47], v[244:247], v[204:207], v[32:47]
	global_load_lds_dwordx4 v190, s[4:5]
	s_add_u32 m0, s8, 0x3000
	v_mfma_f32_32x32x16_bf16 v[16:31], v[240:243], v[208:211], v[16:31]
	global_load_lds_dwordx4 v191, s[4:5]
	s_add_u32 m0, s8, 0x4000
	v_mfma_f32_32x32x16_bf16 v[0:15], v[244:247], v[208:211], v[0:15]
	global_load_lds_dwordx4 v189, s[6:7]
	s_add_u32 m0, s8, 0x5000
	s_add_u32 s4, s4, 0x202000
	s_addc_u32 s5, s5, 0
	global_load_lds_dwordx4 v252, s[6:7]
	s_add_u32 s6, s6, 0x40000
	s_addc_u32 s7, s7, 0
	s_waitcnt lgkmcnt(0)
	ds_read_b128 v[240:243], v188 offset:24576
	ds_read_b128 v[244:247], v188 offset:26624
	v_mfma_f32_32x32x16_bf16 v[112:127], v[132:135], v[140:143], v[112:127]
	ds_read_b128 v[248:251], v131 offset:24576
	ds_read_b128 v[200:203], v131 offset:28672
	v_mfma_f32_32x32x16_bf16 v[96:111], v[136:139], v[140:143], v[96:111]
	ds_read_b128 v[204:207], v131 offset:32768
	ds_read_b128 v[208:211], v131 offset:36864
	v_mfma_f32_32x32x16_bf16 v[80:95], v[132:135], v[180:183], v[80:95]
	v_mfma_f32_32x32x16_bf16 v[64:79], v[136:139], v[180:183], v[64:79]
	v_mfma_f32_32x32x16_bf16 v[48:63], v[132:135], v[184:187], v[48:63]
	v_mfma_f32_32x32x16_bf16 v[32:47], v[136:139], v[184:187], v[32:47]
	v_mfma_f32_32x32x16_bf16 v[16:31], v[132:135], v[236:239], v[16:31]
	v_mfma_f32_32x32x16_bf16 v[0:15], v[136:139], v[236:239], v[0:15]
	s_waitcnt lgkmcnt(0)
	s_waitcnt vmcnt(6)
	s_barrier
	ds_read_b128 v[132:135], v156 offset:49152
	ds_read_b128 v[136:139], v156 offset:51200
	v_mfma_f32_32x32x16_bf16 v[112:127], v[240:243], v[248:251], v[112:127]
	ds_read_b128 v[140:143], v129 offset:49152
	ds_read_b128 v[180:183], v129 offset:53248
	v_mfma_f32_32x32x16_bf16 v[96:111], v[244:247], v[248:251], v[96:111]
	ds_read_b128 v[184:187], v129 offset:57344
	ds_read_b128 v[236:239], v129 offset:61440
	v_mfma_f32_32x32x16_bf16 v[80:95], v[240:243], v[200:203], v[80:95]
	s_add_u32 m0, s8, 0x6000
	v_mfma_f32_32x32x16_bf16 v[64:79], v[244:247], v[200:203], v[64:79]
	global_load_lds_dwordx4 v189, s[4:5]
	s_add_u32 m0, s8, 0x7000
	v_mfma_f32_32x32x16_bf16 v[48:63], v[240:243], v[204:207], v[48:63]
	global_load_lds_dwordx4 v252, s[4:5]
	s_add_u32 m0, s8, 0x8000
	v_mfma_f32_32x32x16_bf16 v[32:47], v[244:247], v[204:207], v[32:47]
	global_load_lds_dwordx4 v190, s[4:5]
	s_add_u32 m0, s8, 0x9000
	v_mfma_f32_32x32x16_bf16 v[16:31], v[240:243], v[208:211], v[16:31]
	global_load_lds_dwordx4 v191, s[4:5]
	s_add_u32 m0, s8, 0xa000
	v_mfma_f32_32x32x16_bf16 v[0:15], v[244:247], v[208:211], v[0:15]
	global_load_lds_dwordx4 v189, s[6:7]
	s_add_u32 m0, s8, 0xb000
	s_add_u32 s4, s4, 0x202000
	s_addc_u32 s5, s5, 0
	global_load_lds_dwordx4 v252, s[6:7]
	s_add_u32 s6, s6, 0x40000
	s_addc_u32 s7, s7, 0
	s_waitcnt lgkmcnt(0)
	ds_read_b128 v[240:243], v188 offset:49152
	ds_read_b128 v[244:247], v188 offset:51200
	v_mfma_f32_32x32x16_bf16 v[112:127], v[132:135], v[140:143], v[112:127]
	ds_read_b128 v[248:251], v131 offset:49152
	ds_read_b128 v[200:203], v131 offset:53248
	v_mfma_f32_32x32x16_bf16 v[96:111], v[136:139], v[140:143], v[96:111]
	ds_read_b128 v[204:207], v131 offset:57344
	ds_read_b128 v[208:211], v131 offset:61440
	v_mfma_f32_32x32x16_bf16 v[80:95], v[132:135], v[180:183], v[80:95]
	v_mfma_f32_32x32x16_bf16 v[64:79], v[136:139], v[180:183], v[64:79]
	v_mfma_f32_32x32x16_bf16 v[48:63], v[132:135], v[184:187], v[48:63]
	v_mfma_f32_32x32x16_bf16 v[32:47], v[136:139], v[184:187], v[32:47]
	v_mfma_f32_32x32x16_bf16 v[16:31], v[132:135], v[236:239], v[16:31]
	v_mfma_f32_32x32x16_bf16 v[0:15], v[136:139], v[236:239], v[0:15]
	s_waitcnt lgkmcnt(0)
	s_waitcnt vmcnt(6)
	s_barrier
	ds_read_b128 v[132:135], v156
	ds_read_b128 v[136:139], v156 offset:2048
	v_mfma_f32_32x32x16_bf16 v[112:127], v[240:243], v[248:251], v[112:127]
	ds_read_b128 v[140:143], v129
	ds_read_b128 v[180:183], v129 offset:4096
	v_mfma_f32_32x32x16_bf16 v[96:111], v[244:247], v[248:251], v[96:111]
	ds_read_b128 v[184:187], v129 offset:8192
	ds_read_b128 v[236:239], v129 offset:12288
	v_mfma_f32_32x32x16_bf16 v[80:95], v[240:243], v[200:203], v[80:95]
	v_mfma_f32_32x32x16_bf16 v[64:79], v[244:247], v[200:203], v[64:79]
	v_mfma_f32_32x32x16_bf16 v[48:63], v[240:243], v[204:207], v[48:63]
	v_mfma_f32_32x32x16_bf16 v[32:47], v[244:247], v[204:207], v[32:47]
	v_mfma_f32_32x32x16_bf16 v[16:31], v[240:243], v[208:211], v[16:31]
	v_mfma_f32_32x32x16_bf16 v[0:15], v[244:247], v[208:211], v[0:15]
	s_waitcnt lgkmcnt(0)
	ds_read_b128 v[240:243], v188
	ds_read_b128 v[244:247], v188 offset:2048
	v_mfma_f32_32x32x16_bf16 v[112:127], v[132:135], v[140:143], v[112:127]
	ds_read_b128 v[248:251], v131
	ds_read_b128 v[200:203], v131 offset:4096
	v_mfma_f32_32x32x16_bf16 v[96:111], v[136:139], v[140:143], v[96:111]
	ds_read_b128 v[204:207], v131 offset:8192
	ds_read_b128 v[208:211], v131 offset:12288
	v_mfma_f32_32x32x16_bf16 v[80:95], v[132:135], v[180:183], v[80:95]
	v_mfma_f32_32x32x16_bf16 v[64:79], v[136:139], v[180:183], v[64:79]
	v_mfma_f32_32x32x16_bf16 v[48:63], v[132:135], v[184:187], v[48:63]
	v_mfma_f32_32x32x16_bf16 v[32:47], v[136:139], v[184:187], v[32:47]
	v_mfma_f32_32x32x16_bf16 v[16:31], v[132:135], v[236:239], v[16:31]
	v_mfma_f32_32x32x16_bf16 v[0:15], v[136:139], v[236:239], v[0:15]
	s_waitcnt lgkmcnt(0)
	s_waitcnt vmcnt(0)
	s_barrier
	ds_read_b128 v[132:135], v156 offset:24576
	ds_read_b128 v[136:139], v156 offset:26624
	v_mfma_f32_32x32x16_bf16 v[112:127], v[240:243], v[248:251], v[112:127]
	ds_read_b128 v[140:143], v129 offset:24576
	ds_read_b128 v[180:183], v129 offset:28672
	v_mfma_f32_32x32x16_bf16 v[96:111], v[244:247], v[248:251], v[96:111]
	ds_read_b128 v[184:187], v129 offset:32768
	ds_read_b128 v[236:239], v129 offset:36864
	v_mfma_f32_32x32x16_bf16 v[80:95], v[240:243], v[200:203], v[80:95]
	v_mfma_f32_32x32x16_bf16 v[64:79], v[244:247], v[200:203], v[64:79]
	v_mfma_f32_32x32x16_bf16 v[48:63], v[240:243], v[204:207], v[48:63]
	v_mfma_f32_32x32x16_bf16 v[32:47], v[244:247], v[204:207], v[32:47]
	v_mfma_f32_32x32x16_bf16 v[16:31], v[240:243], v[208:211], v[16:31]
	v_mfma_f32_32x32x16_bf16 v[0:15], v[244:247], v[208:211], v[0:15]
	s_waitcnt lgkmcnt(0)
	ds_read_b128 v[240:243], v188 offset:24576
	ds_read_b128 v[244:247], v188 offset:26624
	v_mfma_f32_32x32x16_bf16 v[112:127], v[132:135], v[140:143], v[112:127]
	ds_read_b128 v[248:251], v131 offset:24576
	ds_read_b128 v[200:203], v131 offset:28672
	v_mfma_f32_32x32x16_bf16 v[96:111], v[136:139], v[140:143], v[96:111]
	ds_read_b128 v[204:207], v131 offset:32768
	ds_read_b128 v[208:211], v131 offset:36864
	v_mfma_f32_32x32x16_bf16 v[80:95], v[132:135], v[180:183], v[80:95]
	v_mfma_f32_32x32x16_bf16 v[64:79], v[136:139], v[180:183], v[64:79]
	v_mfma_f32_32x32x16_bf16 v[48:63], v[132:135], v[184:187], v[48:63]
	v_mfma_f32_32x32x16_bf16 v[32:47], v[136:139], v[184:187], v[32:47]
	v_mfma_f32_32x32x16_bf16 v[16:31], v[132:135], v[236:239], v[16:31]
	v_mfma_f32_32x32x16_bf16 v[0:15], v[136:139], v[236:239], v[0:15]
	s_waitcnt lgkmcnt(0)
	v_mfma_f32_32x32x16_bf16 v[112:127], v[240:243], v[248:251], v[112:127]
	v_mfma_f32_32x32x16_bf16 v[96:111], v[244:247], v[248:251], v[96:111]
	v_mfma_f32_32x32x16_bf16 v[80:95], v[240:243], v[200:203], v[80:95]
	v_mfma_f32_32x32x16_bf16 v[64:79], v[244:247], v[200:203], v[64:79]
	v_mfma_f32_32x32x16_bf16 v[48:63], v[240:243], v[204:207], v[48:63]
	v_mfma_f32_32x32x16_bf16 v[32:47], v[244:247], v[204:207], v[32:47]
	v_mfma_f32_32x32x16_bf16 v[16:31], v[240:243], v[208:211], v[16:31]
	v_mfma_f32_32x32x16_bf16 v[0:15], v[244:247], v[208:211], v[0:15]
	s_nop 15
	v_or_b32_e32 v190, 8, v150
	v_or_b32_e32 v191, 9, v150
	v_or_b32_e32 v192, 10, v150
	v_or_b32_e32 v193, 11, v150
	v_or_b32_e32 v194, 16, v150
	v_or_b32_e32 v195, 17, v150
	v_or_b32_e32 v200, 18, v150
	v_or_b32_e32 v201, 19, v150
	v_or_b32_e32 v202, 24, v150
	v_or_b32_e32 v203, 25, v150
	v_or_b32_e32 v204, 26, v150
	v_or_b32_e32 v205, 27, v150
	v_or_b32_e32 v206, 32, v150
	v_or_b32_e32 v207, 33, v150
	v_or_b32_e32 v208, 34, v150
	v_or_b32_e32 v209, 35, v150
	v_or_b32_e32 v210, 40, v150
	v_or_b32_e32 v211, 41, v150
	v_or_b32_e32 v212, 42, v150
	v_or_b32_e32 v213, 43, v150
	v_or_b32_e32 v214, 48, v150
	v_or_b32_e32 v215, 49, v150
	v_or_b32_e32 v216, 50, v150
	v_or_b32_e32 v217, 51, v150
	v_or_b32_e32 v218, 56, v150
	v_or_b32_e32 v219, 57, v150
	v_or_b32_e32 v220, 58, v150
	v_or_b32_e32 v221, 59, v150

.LBB0_887:
	s_or_saveexec_b64 s[0:1], s[0:1]
	v_mov_b32_e32 v127, 0
	v_mov_b32_e32 v126, 0
	v_mov_b32_e32 v125, 0
	v_mov_b32_e32 v124, 0
	v_mov_b32_e32 v123, 0
	v_mov_b32_e32 v122, 0
	v_mov_b32_e32 v121, 0
	v_mov_b32_e32 v120, 0
	v_mov_b32_e32 v119, 0
	v_mov_b32_e32 v118, 0
	v_mov_b32_e32 v117, 0
	v_mov_b32_e32 v116, 0
	v_mov_b32_e32 v115, 0
	v_mov_b32_e32 v114, 0
	v_mov_b32_e32 v113, 0
	v_mov_b32_e32 v112, 0
	v_mov_b32_e32 v63, 0
	v_mov_b32_e32 v62, 0
	v_mov_b32_e32 v61, 0
	v_mov_b32_e32 v60, 0
	v_mov_b32_e32 v59, 0
	v_mov_b32_e32 v58, 0
	v_mov_b32_e32 v57, 0
	v_mov_b32_e32 v56, 0
	v_mov_b32_e32 v55, 0
	v_mov_b32_e32 v54, 0
	v_mov_b32_e32 v53, 0
	v_mov_b32_e32 v52, 0
	v_mov_b32_e32 v51, 0
	v_mov_b32_e32 v50, 0
	v_mov_b32_e32 v49, 0
	v_mov_b32_e32 v48, 0
	v_mov_b32_e32 v111, 0
	v_mov_b32_e32 v110, 0
	v_mov_b32_e32 v109, 0
	v_mov_b32_e32 v108, 0
	v_mov_b32_e32 v107, 0
	v_mov_b32_e32 v106, 0
	v_mov_b32_e32 v105, 0
	v_mov_b32_e32 v104, 0
	v_mov_b32_e32 v103, 0
	v_mov_b32_e32 v102, 0
	v_mov_b32_e32 v101, 0
	v_mov_b32_e32 v100, 0
	v_mov_b32_e32 v99, 0
	v_mov_b32_e32 v98, 0
	v_mov_b32_e32 v97, 0
	v_mov_b32_e32 v96, 0
	v_mov_b32_e32 v47, 0
	v_mov_b32_e32 v46, 0
	v_mov_b32_e32 v45, 0
	v_mov_b32_e32 v44, 0
	v_mov_b32_e32 v43, 0
	v_mov_b32_e32 v42, 0
	v_mov_b32_e32 v41, 0
	v_mov_b32_e32 v40, 0
	v_mov_b32_e32 v39, 0
	v_mov_b32_e32 v38, 0
	v_mov_b32_e32 v37, 0
	v_mov_b32_e32 v36, 0
	v_mov_b32_e32 v35, 0
	v_mov_b32_e32 v34, 0
	v_mov_b32_e32 v33, 0
	v_mov_b32_e32 v32, 0
	s_xor_b64 exec, exec, s[0:1]
	s_cbranch_execz .LBB0_891
	v_readfirstlane_b32 s78, v148
	v_readfirstlane_b32 s79, v150
	v_readfirstlane_b32 s76, v178
	v_mbcnt_lo_u32_b32 v164, -1, 0
	v_mbcnt_hi_u32_b32 v164, -1, v164
	s_nop 3
	s_lshl_b32 s78, s78, 14
	s_lshl_b32 s79, s79, 13
	s_add_u32 s72, s90, s78
	s_addc_u32 s73, s91, 0
	s_add_u32 s74, s90, s79
	s_addc_u32 s75, s91, 0
	s_add_u32 s74, s74, 0x1bbc8000
	s_addc_u32 s75, s75, 0
	v_and_b32_e32 v165, 31, v164
	v_lshrrev_b32_e32 v166, 5, v164
	v_bfe_u32 v167, v164, 2, 2
	v_xor_b32_e32 v166, v166, v167
	v_lshlrev_b32_e32 v166, 4, v166
	v_lshl_or_b32 v165, v165, 6, v166
	v_lshrrev_b32_e32 v167, 10, v178
	v_lshrrev_b32_e32 v166, 1, v167
	v_lshl_or_b32 v156, v166, 11, v165
	v_and_b32_e32 v166, 1, v167
	v_lshl_or_b32 v158, v166, 12, v165
	v_or_b32_e32 v158, 0x4000, v158
	v_xor_b32_e32 v157, 32, v156
	v_xor_b32_e32 v159, 32, v158
	v_lshrrev_b32_e32 v165, 2, v164
	v_lshrrev_b32_e32 v166, 4, v164
	v_xor_b32_e32 v166, v166, v164
	v_and_b32_e32 v166, 3, v166
	v_lshlrev_b32_e32 v166, 4, v166
	v_lshl_or_b32 v165, v165, 6, v166
	v_or_b32_e32 v160, v165, v178
	v_add_u32_e32 v161, 0x1000, v160
	v_add_u32_e32 v162, 0x2000, v160
	v_add_u32_e32 v163, 0x3000, v160
	s_add_u32 m0, s76, 0x2000
	s_nop 0
	global_load_lds_dwordx4 v162, s[72:73]
	s_add_u32 m0, s76, 0x3000
	s_nop 0
	global_load_lds_dwordx4 v163, s[72:73]
	s_add_u32 m0, s76, 0x4000
	s_nop 0
	global_load_lds_dwordx4 v160, s[74:75]
	s_add_u32 m0, s76, 0x5000
	s_nop 0
	global_load_lds_dwordx4 v161, s[74:75]
	s_add_u32 s72, s72, 0x202000
	s_addc_u32 s73, s73, 0
	s_add_u32 s74, s74, 0x10000
	s_addc_u32 s75, s75, 0
	s_add_u32 m0, s76, 0x6000
	s_nop 0
	global_load_lds_dwordx4 v160, s[72:73]
	s_add_u32 m0, s76, 0x7000
	s_nop 0
	global_load_lds_dwordx4 v161, s[72:73]
	s_add_u32 m0, s76, 0x8000
	s_nop 0
	global_load_lds_dwordx4 v162, s[72:73]
	s_add_u32 m0, s76, 0x9000
	s_nop 0
	global_load_lds_dwordx4 v163, s[72:73]
	s_add_u32 m0, s76, 0xa000
	s_nop 0
	global_load_lds_dwordx4 v160, s[74:75]
	s_add_u32 m0, s76, 0xb000
	s_nop 0
	global_load_lds_dwordx4 v161, s[74:75]
	s_add_u32 s72, s72, 0x202000
	s_addc_u32 s73, s73, 0
	s_add_u32 s74, s74, 0x10000
	s_addc_u32 s75, s75, 0
	s_add_u32 m0, s76, 0xc000
	s_nop 0
	global_load_lds_dwordx4 v160, s[72:73]
	s_add_u32 m0, s76, 0xd000
	s_nop 0
	global_load_lds_dwordx4 v161, s[72:73]
	s_add_u32 m0, s76, 0xe000
	s_nop 0
	global_load_lds_dwordx4 v162, s[72:73]
	s_add_u32 m0, s76, 0xf000
	s_nop 0
	global_load_lds_dwordx4 v163, s[72:73]
	s_add_u32 m0, s76, 0x10000
	s_nop 0
	global_load_lds_dwordx4 v160, s[74:75]
	s_add_u32 m0, s76, 0x11000
	s_nop 0
	global_load_lds_dwordx4 v161, s[74:75]
	s_add_u32 s72, s72, 0x202000
	s_addc_u32 s73, s73, 0
	s_add_u32 s74, s74, 0x10000
	s_addc_u32 s75, s75, 0
	v_mov_b32_e32 v80, 0
	v_mov_b32_e32 v81, 0
	v_mov_b32_e32 v82, 0
	v_mov_b32_e32 v83, 0
	v_mov_b32_e32 v84, 0
	v_mov_b32_e32 v85, 0
	v_mov_b32_e32 v86, 0
	v_mov_b32_e32 v87, 0
	v_mov_b32_e32 v88, 0
	v_mov_b32_e32 v89, 0
	v_mov_b32_e32 v90, 0
	v_mov_b32_e32 v91, 0
	v_mov_b32_e32 v92, 0
	v_mov_b32_e32 v93, 0
	v_mov_b32_e32 v94, 0
	v_mov_b32_e32 v95, 0
	v_mov_b32_e32 v16, 0
	v_mov_b32_e32 v17, 0
	v_mov_b32_e32 v18, 0
	v_mov_b32_e32 v19, 0
	v_mov_b32_e32 v20, 0
	v_mov_b32_e32 v21, 0
	v_mov_b32_e32 v22, 0
	v_mov_b32_e32 v23, 0
	v_mov_b32_e32 v24, 0
	v_mov_b32_e32 v25, 0
	v_mov_b32_e32 v26, 0
	v_mov_b32_e32 v27, 0
	v_mov_b32_e32 v28, 0
	v_mov_b32_e32 v29, 0
	v_mov_b32_e32 v30, 0
	v_mov_b32_e32 v31, 0
	v_mov_b32_e32 v112, 0
	v_mov_b32_e32 v113, 0
	v_mov_b32_e32 v114, 0
	v_mov_b32_e32 v115, 0
	v_mov_b32_e32 v116, 0
	v_mov_b32_e32 v117, 0
	v_mov_b32_e32 v118, 0
	v_mov_b32_e32 v119, 0
	v_mov_b32_e32 v120, 0
	v_mov_b32_e32 v121, 0
	v_mov_b32_e32 v122, 0
	v_mov_b32_e32 v123, 0
	v_mov_b32_e32 v124, 0
	v_mov_b32_e32 v125, 0
	v_mov_b32_e32 v126, 0
	v_mov_b32_e32 v127, 0
	v_mov_b32_e32 v48, 0
	v_mov_b32_e32 v49, 0
	v_mov_b32_e32 v50, 0
	v_mov_b32_e32 v51, 0
	v_mov_b32_e32 v52, 0
	v_mov_b32_e32 v53, 0
	v_mov_b32_e32 v54, 0
	v_mov_b32_e32 v55, 0
	v_mov_b32_e32 v56, 0
	v_mov_b32_e32 v57, 0
	v_mov_b32_e32 v58, 0
	v_mov_b32_e32 v59, 0
	v_mov_b32_e32 v60, 0
	v_mov_b32_e32 v61, 0
	v_mov_b32_e32 v62, 0
	v_mov_b32_e32 v63, 0
	v_mov_b32_e32 v64, 0
	v_mov_b32_e32 v65, 0
	v_mov_b32_e32 v66, 0
	v_mov_b32_e32 v67, 0
	v_mov_b32_e32 v68, 0
	v_mov_b32_e32 v69, 0
	v_mov_b32_e32 v70, 0
	v_mov_b32_e32 v71, 0
	v_mov_b32_e32 v72, 0
	v_mov_b32_e32 v73, 0
	v_mov_b32_e32 v74, 0
	v_mov_b32_e32 v75, 0
	v_mov_b32_e32 v76, 0
	v_mov_b32_e32 v77, 0
	v_mov_b32_e32 v78, 0
	v_mov_b32_e32 v79, 0
	v_mov_b32_e32 v0, 0
	v_mov_b32_e32 v1, 0
	v_mov_b32_e32 v2, 0
	v_mov_b32_e32 v3, 0
	v_mov_b32_e32 v4, 0
	v_mov_b32_e32 v5, 0
	v_mov_b32_e32 v6, 0
	v_mov_b32_e32 v7, 0
	v_mov_b32_e32 v8, 0
	v_mov_b32_e32 v9, 0
	v_mov_b32_e32 v10, 0
	v_mov_b32_e32 v11, 0
	v_mov_b32_e32 v12, 0
	v_mov_b32_e32 v13, 0
	v_mov_b32_e32 v14, 0
	v_mov_b32_e32 v15, 0
	v_mov_b32_e32 v96, 0
	v_mov_b32_e32 v97, 0
	v_mov_b32_e32 v98, 0
	v_mov_b32_e32 v99, 0
	v_mov_b32_e32 v100, 0
	v_mov_b32_e32 v101, 0
	v_mov_b32_e32 v102, 0
	v_mov_b32_e32 v103, 0
	v_mov_b32_e32 v104, 0
	v_mov_b32_e32 v105, 0
	v_mov_b32_e32 v106, 0
	v_mov_b32_e32 v107, 0
	v_mov_b32_e32 v108, 0
	v_mov_b32_e32 v109, 0
	v_mov_b32_e32 v110, 0
	v_mov_b32_e32 v111, 0
	v_mov_b32_e32 v32, 0
	v_mov_b32_e32 v33, 0
	v_mov_b32_e32 v34, 0
	v_mov_b32_e32 v35, 0
	v_mov_b32_e32 v36, 0
	v_mov_b32_e32 v37, 0
	v_mov_b32_e32 v38, 0
	v_mov_b32_e32 v39, 0
	v_mov_b32_e32 v40, 0
	v_mov_b32_e32 v41, 0
	v_mov_b32_e32 v42, 0
	v_mov_b32_e32 v43, 0
	v_mov_b32_e32 v44, 0
	v_mov_b32_e32 v45, 0
	v_mov_b32_e32 v46, 0
	v_mov_b32_e32 v47, 0
	s_waitcnt vmcnt(12)
	s_barrier
	ds_read_b128 v[200:203], v158
	ds_read_b128 v[204:207], v158 offset:2048
	ds_read_b128 v[208:211], v156
	ds_read_b128 v[212:215], v156 offset:4096
	ds_read_b128 v[216:219], v156 offset:8192
	ds_read_b128 v[220:223], v156 offset:12288
	s_waitcnt lgkmcnt(0)
	s_mov_b32 s77, 9
.Lgemm_p6_loop:
	ds_read_b128 v[224:227], v159
	ds_read_b128 v[228:231], v159 offset:2048
	v_mfma_f32_32x32x16_bf16 v[80:95], v[200:203], v[208:211], v[80:95]
	ds_read_b128 v[232:235], v157
	ds_read_b128 v[236:239], v157 offset:4096
	v_mfma_f32_32x32x16_bf16 v[64:79], v[204:207], v[208:211], v[64:79]
	ds_read_b128 v[240:243], v157 offset:8192
	ds_read_b128 v[152:155], v157 offset:12288
	v_mfma_f32_32x32x16_bf16 v[16:31], v[200:203], v[212:215], v[16:31]
	v_mfma_f32_32x32x16_bf16 v[0:15], v[204:207], v[212:215], v[0:15]
	v_mfma_f32_32x32x16_bf16 v[112:127], v[200:203], v[216:219], v[112:127]
	v_mfma_f32_32x32x16_bf16 v[96:111], v[204:207], v[216:219], v[96:111]
	v_mfma_f32_32x32x16_bf16 v[48:63], v[200:203], v[220:223], v[48:63]
	v_mfma_f32_32x32x16_bf16 v[32:47], v[204:207], v[220:223], v[32:47]
	s_waitcnt lgkmcnt(0)
	s_waitcnt vmcnt(6)
	s_barrier
	ds_read_b128 v[200:203], v158 offset:24576
	ds_read_b128 v[204:207], v158 offset:26624
	v_mfma_f32_32x32x16_bf16 v[80:95], v[224:227], v[232:235], v[80:95]
	ds_read_b128 v[208:211], v156 offset:24576
	ds_read_b128 v[212:215], v156 offset:28672
	v_mfma_f32_32x32x16_bf16 v[64:79], v[228:231], v[232:235], v[64:79]
	ds_read_b128 v[216:219], v156 offset:32768
	ds_read_b128 v[220:223], v156 offset:36864
	v_mfma_f32_32x32x16_bf16 v[16:31], v[224:227], v[236:239], v[16:31]
	s_add_u32 m0, s76, 0x0
	v_mfma_f32_32x32x16_bf16 v[0:15], v[228:231], v[236:239], v[0:15]
	global_load_lds_dwordx4 v160, s[72:73]
	s_add_u32 m0, s76, 0x1000
	v_mfma_f32_32x32x16_bf16 v[112:127], v[224:227], v[240:243], v[112:127]
	global_load_lds_dwordx4 v161, s[72:73]
	s_add_u32 m0, s76, 0x2000
	v_mfma_f32_32x32x16_bf16 v[96:111], v[228:231], v[240:243], v[96:111]
	global_load_lds_dwordx4 v162, s[72:73]
	s_add_u32 m0, s76, 0x3000
	v_mfma_f32_32x32x16_bf16 v[48:63], v[224:227], v[152:155], v[48:63]
	global_load_lds_dwordx4 v163, s[72:73]
	s_add_u32 m0, s76, 0x4000
	v_mfma_f32_32x32x16_bf16 v[32:47], v[228:231], v[152:155], v[32:47]
	global_load_lds_dwordx4 v160, s[74:75]
	s_add_u32 m0, s76, 0x5000
	s_add_u32 s72, s72, 0x202000
	s_addc_u32 s73, s73, 0
	global_load_lds_dwordx4 v161, s[74:75]
	s_add_u32 s74, s74, 0x10000
	s_addc_u32 s75, s75, 0
	s_waitcnt lgkmcnt(0)
	ds_read_b128 v[224:227], v159 offset:24576
	ds_read_b128 v[228:231], v159 offset:26624
	v_mfma_f32_32x32x16_bf16 v[80:95], v[200:203], v[208:211], v[80:95]
	ds_read_b128 v[232:235], v157 offset:24576
	ds_read_b128 v[236:239], v157 offset:28672
	v_mfma_f32_32x32x16_bf16 v[64:79], v[204:207], v[208:211], v[64:79]
	ds_read_b128 v[240:243], v157 offset:32768
	ds_read_b128 v[152:155], v157 offset:36864
	v_mfma_f32_32x32x16_bf16 v[16:31], v[200:203], v[212:215], v[16:31]
	v_mfma_f32_32x32x16_bf16 v[0:15], v[204:207], v[212:215], v[0:15]
	v_mfma_f32_32x32x16_bf16 v[112:127], v[200:203], v[216:219], v[112:127]
	v_mfma_f32_32x32x16_bf16 v[96:111], v[204:207], v[216:219], v[96:111]
	v_mfma_f32_32x32x16_bf16 v[48:63], v[200:203], v[220:223], v[48:63]
	v_mfma_f32_32x32x16_bf16 v[32:47], v[204:207], v[220:223], v[32:47]
	s_waitcnt lgkmcnt(0)
	s_waitcnt vmcnt(6)
	s_barrier
	ds_read_b128 v[200:203], v158 offset:49152
	ds_read_b128 v[204:207], v158 offset:51200
	v_mfma_f32_32x32x16_bf16 v[80:95], v[224:227], v[232:235], v[80:95]
	ds_read_b128 v[208:211], v156 offset:49152
	ds_read_b128 v[212:215], v156 offset:53248
	v_mfma_f32_32x32x16_bf16 v[64:79], v[228:231], v[232:235], v[64:79]
	ds_read_b128 v[216:219], v156 offset:57344
	ds_read_b128 v[220:223], v156 offset:61440
	v_mfma_f32_32x32x16_bf16 v[16:31], v[224:227], v[236:239], v[16:31]
	s_add_u32 m0, s76, 0x6000
	v_mfma_f32_32x32x16_bf16 v[0:15], v[228:231], v[236:239], v[0:15]
	global_load_lds_dwordx4 v160, s[72:73]
	s_add_u32 m0, s76, 0x7000
	v_mfma_f32_32x32x16_bf16 v[112:127], v[224:227], v[240:243], v[112:127]
	global_load_lds_dwordx4 v161, s[72:73]
	s_add_u32 m0, s76, 0x8000
	v_mfma_f32_32x32x16_bf16 v[96:111], v[228:231], v[240:243], v[96:111]
	global_load_lds_dwordx4 v162, s[72:73]
	s_add_u32 m0, s76, 0x9000
	v_mfma_f32_32x32x16_bf16 v[48:63], v[224:227], v[152:155], v[48:63]
	global_load_lds_dwordx4 v163, s[72:73]
	s_add_u32 m0, s76, 0xa000
	v_mfma_f32_32x32x16_bf16 v[32:47], v[228:231], v[152:155], v[32:47]
	global_load_lds_dwordx4 v160, s[74:75]
	s_add_u32 m0, s76, 0xb000
	s_add_u32 s72, s72, 0x202000
	s_addc_u32 s73, s73, 0
	global_load_lds_dwordx4 v161, s[74:75]
	s_add_u32 s74, s74, 0x10000
	s_addc_u32 s75, s75, 0
	s_waitcnt lgkmcnt(0)
	ds_read_b128 v[224:227], v159 offset:49152
	ds_read_b128 v[228:231], v159 offset:51200
	v_mfma_f32_32x32x16_bf16 v[80:95], v[200:203], v[208:211], v[80:95]
	ds_read_b128 v[232:235], v157 offset:49152
	ds_read_b128 v[236:239], v157 offset:53248
	v_mfma_f32_32x32x16_bf16 v[64:79], v[204:207], v[208:211], v[64:79]
	ds_read_b128 v[240:243], v157 offset:57344
	ds_read_b128 v[152:155], v157 offset:61440
	v_mfma_f32_32x32x16_bf16 v[16:31], v[200:203], v[212:215], v[16:31]
	v_mfma_f32_32x32x16_bf16 v[0:15], v[204:207], v[212:215], v[0:15]
	v_mfma_f32_32x32x16_bf16 v[112:127], v[200:203], v[216:219], v[112:127]
	v_mfma_f32_32x32x16_bf16 v[96:111], v[204:207], v[216:219], v[96:111]
	v_mfma_f32_32x32x16_bf16 v[48:63], v[200:203], v[220:223], v[48:63]
	v_mfma_f32_32x32x16_bf16 v[32:47], v[204:207], v[220:223], v[32:47]
	s_waitcnt lgkmcnt(0)
	s_waitcnt vmcnt(6)
	s_barrier
	ds_read_b128 v[200:203], v158
	ds_read_b128 v[204:207], v158 offset:2048
	v_mfma_f32_32x32x16_bf16 v[80:95], v[224:227], v[232:235], v[80:95]
	ds_read_b128 v[208:211], v156
	ds_read_b128 v[212:215], v156 offset:4096
	v_mfma_f32_32x32x16_bf16 v[64:79], v[228:231], v[232:235], v[64:79]
	ds_read_b128 v[216:219], v156 offset:8192
	ds_read_b128 v[220:223], v156 offset:12288
	v_mfma_f32_32x32x16_bf16 v[16:31], v[224:227], v[236:239], v[16:31]
	s_add_u32 m0, s76, 0xc000
	v_mfma_f32_32x32x16_bf16 v[0:15], v[228:231], v[236:239], v[0:15]
	global_load_lds_dwordx4 v160, s[72:73]
	s_add_u32 m0, s76, 0xd000
	v_mfma_f32_32x32x16_bf16 v[112:127], v[224:227], v[240:243], v[112:127]
	global_load_lds_dwordx4 v161, s[72:73]
	s_add_u32 m0, s76, 0xe000
	v_mfma_f32_32x32x16_bf16 v[96:111], v[228:231], v[240:243], v[96:111]
	global_load_lds_dwordx4 v162, s[72:73]
	s_add_u32 m0, s76, 0xf000
	v_mfma_f32_32x32x16_bf16 v[48:63], v[224:227], v[152:155], v[48:63]
	global_load_lds_dwordx4 v163, s[72:73]
	s_add_u32 m0, s76, 0x10000
	v_mfma_f32_32x32x16_bf16 v[32:47], v[228:231], v[152:155], v[32:47]
	global_load_lds_dwordx4 v160, s[74:75]
	s_add_u32 m0, s76, 0x11000
	s_add_u32 s72, s72, 0x202000
	s_addc_u32 s73, s73, 0
	global_load_lds_dwordx4 v161, s[74:75]
	s_add_u32 s74, s74, 0x10000
	s_addc_u32 s75, s75, 0
	s_waitcnt lgkmcnt(0)
	s_sub_i32 s77, s77, 1
	s_cmp_lg_u32 s77, 0
	s_cbranch_scc1 .Lgemm_p6_loop
	ds_read_b128 v[224:227], v159
	ds_read_b128 v[228:231], v159 offset:2048
	v_mfma_f32_32x32x16_bf16 v[80:95], v[200:203], v[208:211], v[80:95]
	ds_read_b128 v[232:235], v157
	ds_read_b128 v[236:239], v157 offset:4096
	v_mfma_f32_32x32x16_bf16 v[64:79], v[204:207], v[208:211], v[64:79]
	ds_read_b128 v[240:243], v157 offset:8192
	ds_read_b128 v[152:155], v157 offset:12288
	v_mfma_f32_32x32x16_bf16 v[16:31], v[200:203], v[212:215], v[16:31]
	v_mfma_f32_32x32x16_bf16 v[0:15], v[204:207], v[212:215], v[0:15]
	v_mfma_f32_32x32x16_bf16 v[112:127], v[200:203], v[216:219], v[112:127]
	v_mfma_f32_32x32x16_bf16 v[96:111], v[204:207], v[216:219], v[96:111]
	v_mfma_f32_32x32x16_bf16 v[48:63], v[200:203], v[220:223], v[48:63]
	v_mfma_f32_32x32x16_bf16 v[32:47], v[204:207], v[220:223], v[32:47]
	s_waitcnt lgkmcnt(0)
	s_waitcnt vmcnt(6)
	s_barrier
	ds_read_b128 v[200:203], v158 offset:24576
	ds_read_b128 v[204:207], v158 offset:26624
	v_mfma_f32_32x32x16_bf16 v[80:95], v[224:227], v[232:235], v[80:95]
	ds_read_b128 v[208:211], v156 offset:24576
	ds_read_b128 v[212:215], v156 offset:28672
	v_mfma_f32_32x32x16_bf16 v[64:79], v[228:231], v[232:235], v[64:79]
	ds_read_b128 v[216:219], v156 offset:32768
	ds_read_b128 v[220:223], v156 offset:36864
	v_mfma_f32_32x32x16_bf16 v[16:31], v[224:227], v[236:239], v[16:31]
	s_add_u32 m0, s76, 0x0
	v_mfma_f32_32x32x16_bf16 v[0:15], v[228:231], v[236:239], v[0:15]
	global_load_lds_dwordx4 v160, s[72:73]
	s_add_u32 m0, s76, 0x1000
	v_mfma_f32_32x32x16_bf16 v[112:127], v[224:227], v[240:243], v[112:127]
	global_load_lds_dwordx4 v161, s[72:73]
	s_add_u32 m0, s76, 0x2000
	v_mfma_f32_32x32x16_bf16 v[96:111], v[228:231], v[240:243], v[96:111]
	global_load_lds_dwordx4 v162, s[72:73]
	s_add_u32 m0, s76, 0x3000
	v_mfma_f32_32x32x16_bf16 v[48:63], v[224:227], v[152:155], v[48:63]
	global_load_lds_dwordx4 v163, s[72:73]
	s_add_u32 m0, s76, 0x4000
	v_mfma_f32_32x32x16_bf16 v[32:47], v[228:231], v[152:155], v[32:47]
	global_load_lds_dwordx4 v160, s[74:75]
	s_add_u32 m0, s76, 0x5000
	s_add_u32 s72, s72, 0x202000
	s_addc_u32 s73, s73, 0
	global_load_lds_dwordx4 v161, s[74:75]
	s_add_u32 s74, s74, 0x10000
	s_addc_u32 s75, s75, 0
	s_waitcnt lgkmcnt(0)
	ds_read_b128 v[224:227], v159 offset:24576
	ds_read_b128 v[228:231], v159 offset:26624
	v_mfma_f32_32x32x16_bf16 v[80:95], v[200:203], v[208:211], v[80:95]
	ds_read_b128 v[232:235], v157 offset:24576
	ds_read_b128 v[236:239], v157 offset:28672
	v_mfma_f32_32x32x16_bf16 v[64:79], v[204:207], v[208:211], v[64:79]
	ds_read_b128 v[240:243], v157 offset:32768
	ds_read_b128 v[152:155], v157 offset:36864
	v_mfma_f32_32x32x16_bf16 v[16:31], v[200:203], v[212:215], v[16:31]
	v_mfma_f32_32x32x16_bf16 v[0:15], v[204:207], v[212:215], v[0:15]
	v_mfma_f32_32x32x16_bf16 v[112:127], v[200:203], v[216:219], v[112:127]
	v_mfma_f32_32x32x16_bf16 v[96:111], v[204:207], v[216:219], v[96:111]
	v_mfma_f32_32x32x16_bf16 v[48:63], v[200:203], v[220:223], v[48:63]
	v_mfma_f32_32x32x16_bf16 v[32:47], v[204:207], v[220:223], v[32:47]
	s_waitcnt lgkmcnt(0)
	s_waitcnt vmcnt(6)
	s_barrier
	ds_read_b128 v[200:203], v158 offset:49152
	ds_read_b128 v[204:207], v158 offset:51200
	v_mfma_f32_32x32x16_bf16 v[80:95], v[224:227], v[232:235], v[80:95]
	ds_read_b128 v[208:211], v156 offset:49152
	ds_read_b128 v[212:215], v156 offset:53248
	v_mfma_f32_32x32x16_bf16 v[64:79], v[228:231], v[232:235], v[64:79]
	ds_read_b128 v[216:219], v156 offset:57344
	ds_read_b128 v[220:223], v156 offset:61440
	v_mfma_f32_32x32x16_bf16 v[16:31], v[224:227], v[236:239], v[16:31]
	s_add_u32 m0, s76, 0x6000
	v_mfma_f32_32x32x16_bf16 v[0:15], v[228:231], v[236:239], v[0:15]
	global_load_lds_dwordx4 v160, s[72:73]
	s_add_u32 m0, s76, 0x7000
	v_mfma_f32_32x32x16_bf16 v[112:127], v[224:227], v[240:243], v[112:127]
	global_load_lds_dwordx4 v161, s[72:73]
	s_add_u32 m0, s76, 0x8000
	v_mfma_f32_32x32x16_bf16 v[96:111], v[228:231], v[240:243], v[96:111]
	global_load_lds_dwordx4 v162, s[72:73]
	s_add_u32 m0, s76, 0x9000
	v_mfma_f32_32x32x16_bf16 v[48:63], v[224:227], v[152:155], v[48:63]
	global_load_lds_dwordx4 v163, s[72:73]
	s_add_u32 m0, s76, 0xa000
	v_mfma_f32_32x32x16_bf16 v[32:47], v[228:231], v[152:155], v[32:47]
	global_load_lds_dwordx4 v160, s[74:75]
	s_add_u32 m0, s76, 0xb000
	s_add_u32 s72, s72, 0x202000
	s_addc_u32 s73, s73, 0
	global_load_lds_dwordx4 v161, s[74:75]
	s_add_u32 s74, s74, 0x10000
	s_addc_u32 s75, s75, 0
	s_waitcnt lgkmcnt(0)
	ds_read_b128 v[224:227], v159 offset:49152
	ds_read_b128 v[228:231], v159 offset:51200
	v_mfma_f32_32x32x16_bf16 v[80:95], v[200:203], v[208:211], v[80:95]
	ds_read_b128 v[232:235], v157 offset:49152
	ds_read_b128 v[236:239], v157 offset:53248
	v_mfma_f32_32x32x16_bf16 v[64:79], v[204:207], v[208:211], v[64:79]
	ds_read_b128 v[240:243], v157 offset:57344
	ds_read_b128 v[152:155], v157 offset:61440
	v_mfma_f32_32x32x16_bf16 v[16:31], v[200:203], v[212:215], v[16:31]
	v_mfma_f32_32x32x16_bf16 v[0:15], v[204:207], v[212:215], v[0:15]
	v_mfma_f32_32x32x16_bf16 v[112:127], v[200:203], v[216:219], v[112:127]
	v_mfma_f32_32x32x16_bf16 v[96:111], v[204:207], v[216:219], v[96:111]
	v_mfma_f32_32x32x16_bf16 v[48:63], v[200:203], v[220:223], v[48:63]
	v_mfma_f32_32x32x16_bf16 v[32:47], v[204:207], v[220:223], v[32:47]
	s_waitcnt lgkmcnt(0)
	s_waitcnt vmcnt(6)
	s_barrier
	ds_read_b128 v[200:203], v158
	ds_read_b128 v[204:207], v158 offset:2048
	v_mfma_f32_32x32x16_bf16 v[80:95], v[224:227], v[232:235], v[80:95]
	ds_read_b128 v[208:211], v156
	ds_read_b128 v[212:215], v156 offset:4096
	v_mfma_f32_32x32x16_bf16 v[64:79], v[228:231], v[232:235], v[64:79]
	ds_read_b128 v[216:219], v156 offset:8192
	ds_read_b128 v[220:223], v156 offset:12288
	v_mfma_f32_32x32x16_bf16 v[16:31], v[224:227], v[236:239], v[16:31]
	v_mfma_f32_32x32x16_bf16 v[0:15], v[228:231], v[236:239], v[0:15]
	v_mfma_f32_32x32x16_bf16 v[112:127], v[224:227], v[240:243], v[112:127]
	v_mfma_f32_32x32x16_bf16 v[96:111], v[228:231], v[240:243], v[96:111]
	v_mfma_f32_32x32x16_bf16 v[48:63], v[224:227], v[152:155], v[48:63]
	v_mfma_f32_32x32x16_bf16 v[32:47], v[228:231], v[152:155], v[32:47]
	s_waitcnt lgkmcnt(0)
	ds_read_b128 v[224:227], v159
	ds_read_b128 v[228:231], v159 offset:2048
	v_mfma_f32_32x32x16_bf16 v[80:95], v[200:203], v[208:211], v[80:95]
	ds_read_b128 v[232:235], v157
	ds_read_b128 v[236:239], v157 offset:4096
	v_mfma_f32_32x32x16_bf16 v[64:79], v[204:207], v[208:211], v[64:79]
	ds_read_b128 v[240:243], v157 offset:8192
	ds_read_b128 v[152:155], v157 offset:12288
	v_mfma_f32_32x32x16_bf16 v[16:31], v[200:203], v[212:215], v[16:31]
	v_mfma_f32_32x32x16_bf16 v[0:15], v[204:207], v[212:215], v[0:15]
	v_mfma_f32_32x32x16_bf16 v[112:127], v[200:203], v[216:219], v[112:127]
	v_mfma_f32_32x32x16_bf16 v[96:111], v[204:207], v[216:219], v[96:111]
	v_mfma_f32_32x32x16_bf16 v[48:63], v[200:203], v[220:223], v[48:63]
	v_mfma_f32_32x32x16_bf16 v[32:47], v[204:207], v[220:223], v[32:47]
	s_waitcnt lgkmcnt(0)
	s_waitcnt vmcnt(0)
	s_barrier
	ds_read_b128 v[200:203], v158 offset:24576
	ds_read_b128 v[204:207], v158 offset:26624
	v_mfma_f32_32x32x16_bf16 v[80:95], v[224:227], v[232:235], v[80:95]
	ds_read_b128 v[208:211], v156 offset:24576
	ds_read_b128 v[212:215], v156 offset:28672
	v_mfma_f32_32x32x16_bf16 v[64:79], v[228:231], v[232:235], v[64:79]
	ds_read_b128 v[216:219], v156 offset:32768
	ds_read_b128 v[220:223], v156 offset:36864
	v_mfma_f32_32x32x16_bf16 v[16:31], v[224:227], v[236:239], v[16:31]
	v_mfma_f32_32x32x16_bf16 v[0:15], v[228:231], v[236:239], v[0:15]
	v_mfma_f32_32x32x16_bf16 v[112:127], v[224:227], v[240:243], v[112:127]
	v_mfma_f32_32x32x16_bf16 v[96:111], v[228:231], v[240:243], v[96:111]
	v_mfma_f32_32x32x16_bf16 v[48:63], v[224:227], v[152:155], v[48:63]
	v_mfma_f32_32x32x16_bf16 v[32:47], v[228:231], v[152:155], v[32:47]
	s_waitcnt lgkmcnt(0)
	ds_read_b128 v[224:227], v159 offset:24576
	ds_read_b128 v[228:231], v159 offset:26624
	v_mfma_f32_32x32x16_bf16 v[80:95], v[200:203], v[208:211], v[80:95]
	ds_read_b128 v[232:235], v157 offset:24576
	ds_read_b128 v[236:239], v157 offset:28672
	v_mfma_f32_32x32x16_bf16 v[64:79], v[204:207], v[208:211], v[64:79]
	ds_read_b128 v[240:243], v157 offset:32768
	ds_read_b128 v[152:155], v157 offset:36864
	v_mfma_f32_32x32x16_bf16 v[16:31], v[200:203], v[212:215], v[16:31]
	v_mfma_f32_32x32x16_bf16 v[0:15], v[204:207], v[212:215], v[0:15]
	v_mfma_f32_32x32x16_bf16 v[112:127], v[200:203], v[216:219], v[112:127]
	v_mfma_f32_32x32x16_bf16 v[96:111], v[204:207], v[216:219], v[96:111]
	v_mfma_f32_32x32x16_bf16 v[48:63], v[200:203], v[220:223], v[48:63]
	v_mfma_f32_32x32x16_bf16 v[32:47], v[204:207], v[220:223], v[32:47]
	s_waitcnt lgkmcnt(0)
	v_mfma_f32_32x32x16_bf16 v[80:95], v[224:227], v[232:235], v[80:95]
	v_mfma_f32_32x32x16_bf16 v[64:79], v[228:231], v[232:235], v[64:79]
	v_mfma_f32_32x32x16_bf16 v[16:31], v[224:227], v[236:239], v[16:31]
	v_mfma_f32_32x32x16_bf16 v[0:15], v[228:231], v[236:239], v[0:15]
	v_mfma_f32_32x32x16_bf16 v[112:127], v[224:227], v[240:243], v[112:127]
	v_mfma_f32_32x32x16_bf16 v[96:111], v[228:231], v[240:243], v[96:111]
	v_mfma_f32_32x32x16_bf16 v[48:63], v[224:227], v[152:155], v[48:63]
	v_mfma_f32_32x32x16_bf16 v[32:47], v[228:231], v[152:155], v[32:47]
	s_nop 15
